# P1: weight transposes (W_out, W_up, W_down) rewritten as a software-pipelined item loop: two items' loads in flight, LDS reads back to back with counted waits, one straight-line variant per item count
# speedup vs baseline: 1.0133x; 1.0030x over previous
; __device__ __forceinline__ int wup_src(int p0) { const int j = p0 >> 8, c = p0 & 255; return (c < 128) ? 128 * j + c : DFF + 128 * j + (c - 128); }
; __device__ __forceinline__ void transposes(const Params& p, LAS unsigned char* lds, int it_begin, int it_end, int gw, int NGW, int lane, int wave) {
;     ...
;     for (int it = it_begin + gw; it < it_end; it += NGW) {
;         int r = it;
;         if (r < I_IN) { const int kb = r / 96, nb = r % 96; transpose_item(p.w_in, DIN, 1024, (bf16_t*)(p.ws + WS_WIN), 32 * nb, win_src(32 * nb), 64 * kb, scr, lane); continue; } r -= I_IN;
;         if (r < I_OUT) { const int kb = r / 32, nb = r % 32; transpose_item(p.w_out, 1024, 1024, (bf16_t*)(p.ws + WS_WOUT), 32 * nb, 32 * nb, 64 * kb, scr, lane); continue; } r -= I_OUT;
;         if (r < I_UP) { const int kb = r / 176, nb = r % 176; transpose_item(p.w_up, 2 * DFF, 1024, (bf16_t*)(p.ws + WS_WUP), 32 * nb, wup_src(32 * nb), 64 * kb, scr, lane); continue; } r -= I_UP;
;         { const int kb = r / 32, nb = r % 32; transpose_item(p.w_down, 1024, DFF, (bf16_t*)(p.ws + WS_WDOWN), 32 * nb, 32 * nb, 64 * kb, scr, lane); }
; __device__ __forceinline__ void phase1(const Params& p, LAS unsigned char* lds, int tid, int lane, int wave) {
;     ...
;     if (gridDim.x == 256) {
;         if (blockIdx.x < 176) transposes(p, lds, NIT_IN + 2240, NIT_ALL, blockIdx.x * 8 + wave, 176 * 8, lane, wave);
;         else transposes(p, lds, NIT_IN, NIT_IN + 2240, (blockIdx.x - 176) * 8 + wave, 80 * 8, lane, wave);
;     } else transposes(p, lds, gridDim.x > 192 ? NIT_IN : 0, NIT_ALL, blockIdx.x * 8 + wave, gridDim.x * 8, lane, wave);
.LBB0_137:
	s_andn2_b64 vcc, exec, s[6:7]
	s_cbranch_vccnz .LBB0_184
	v_and_b32_e32 v0, 31, v208
	v_lshlrev_b32_e32 v0, 2, v0
	v_lshrrev_b32_e32 v1, 5, v154
	v_lshrrev_b32_e32 v2, 3, v154
	v_and_b32_e32 v3, 7, v208
	v_mul_u32_u24_e32 v6, 0x420, v3
	v_lshlrev_b32_e32 v3, 4, v3
	s_mul_i32 s0, s58, 0x2200
	v_mul_u32_u24_e32 v4, 0x84, v1
	v_add3_u32 v7, s0, v0, v4
	v_add_u32_e32 v8, 0x400, v7
	v_add_u32_e32 v9, 0x800, v7
	v_add_u32_e32 v10, 0xc00, v7
	v_add_u32_e32 v11, 0x1000, v7
	v_add_u32_e32 v12, 0x1400, v7
	v_add_u32_e32 v13, 0x1800, v7
	v_add_u32_e32 v14, 0x1c00, v7
	v_lshlrev_b32_e32 v4, 2, v2
	v_add3_u32 v5, s0, v6, v4
	s_mov_b32 s8, s30
	s_and_b32 s9, s31, 0xffff
	s_brev_b32 s10, -2
	s_mov_b32 s11, 0x20000
	s_lshl_b32 s4, s2, 3
	s_add_i32 s4, s4, s58
	s_cmpk_gt_u32 s2, 0xaf
	s_cbranch_scc1 .Lp1_grpB
	s_addk_i32 s4, 0xec0
	s_cmpk_lt_u32 s4, 0x1300
	s_cbranch_scc1 .Lp1_n2
	s_branch .Lp1_n1
.Lp1_grpB:
	s_addk_i32 s4, 0x80
	s_cmpk_lt_u32 s4, 0x740
	s_cbranch_scc1 .Lp1_n4
	s_branch .Lp1_n3
.Lp1_n1:
	s_mov_b32 s22, s4
	s_addk_i32 s22, 0xfa00
	s_cmpk_lt_u32 s22, 0x200
	s_cbranch_scc0 .Lp1p_up1_0
	s_lshr_b32 s23, s22, 5
	s_and_b32 s28, s22, 31
	s_lshl_b32 s29, s23, 18
	s_lshl_b32 s49, s28, 7
	s_add_i32 s29, s29, s49
	s_add_u32 s12, s42, s29
	s_addc_u32 s13, s43, 0
	s_movk_i32 s14, 0x1000
	s_lshl_b32 s29, s28, 16
	s_lshl_b32 s49, s23, 7
	s_add_i32 s29, s29, s49
	s_add_i32 s15, s29, 0xc00000
	s_movk_i32 s16, 0x800
	s_branch .Lp1p_done1_0
.Lp1p_up1_0:
	s_addk_i32 s22, 0xfe00
	s_cmpk_lt_u32 s22, 0xb00
	s_cbranch_scc0 .Lp1p_dn1_0
	s_mul_hi_u32 s23, s22, 0x1745d18
	s_mul_i32 s28, s23, 0xb0
	s_sub_i32 s28, s22, s28
	s_lshr_b32 s29, s28, 3
	s_lshl_b32 s29, s29, 7
	s_and_b32 s49, s28, 7
	s_lshl_b32 s49, s49, 5
	s_add_i32 s29, s29, s49
	s_cmpk_lt_u32 s49, 0x80
	s_cbranch_scc1 .Lp1p_c1_0
	s_addk_i32 s29, 0xa80
.Lp1p_c1_0:
	s_lshl_b32 s29, s29, 2
	s_mul_i32 s49, s23, 0x160000
	s_add_i32 s29, s29, s49
	s_add_u32 s12, s44, s29
	s_addc_u32 s13, s45, 0
	s_movk_i32 s14, 0x5800
	s_lshl_b32 s29, s28, 16
	s_lshl_b32 s49, s23, 7
	s_add_i32 s29, s29, s49
	s_add_i32 s15, s29, 0xe00000
	s_movk_i32 s16, 0x800
	s_branch .Lp1p_done1_0
.Lp1p_dn1_0:
	s_addk_i32 s22, 0xf500
	s_lshr_b32 s23, s22, 5
	s_and_b32 s28, s22, 31
	s_lshl_b32 s29, s23, 18
	s_lshl_b32 s49, s28, 7
	s_add_i32 s29, s29, s49
	s_add_u32 s12, s46, s29
	s_addc_u32 s13, s47, 0
	s_movk_i32 s14, 0x1000
	s_mul_i32 s29, s28, 0x2c000
	s_lshl_b32 s49, s23, 7
	s_add_i32 s29, s29, s49
	s_add_i32 s15, s29, 0x1900000
	s_movk_i32 s16, 0x1600
; #define LAS __attribute__((address_space(3)))
; __device__ __forceinline__ unsigned pk2(float lo, float hi) { return pg8::cvt_pk_bf16(lo, hi); }
; __device__ __forceinline__ void transpose_item(const float* W, int N, int K, bf16_t* WT, int dstrow0, int srccol0, int k0, LAS float* scr, int lane) {
;     float tv[32];
;     { const float* wp = W + (size_t)(k0 + (lane >> 5)) * N + srccol0 + (lane & 31);
; #pragma unroll
;       for (int i = 0; i < 32; ++i) tv[i] = __builtin_nontemporal_load(wp + (size_t)(2 * i) * N); }
; #pragma unroll
;     for (int i = 0; i < 32; ++i) scr[(2 * i + (lane >> 5)) * 33 + (lane & 31)] = tv[i];
;     asm volatile("s_waitcnt lgkmcnt(0)" ::: "memory");
;     const int c = lane & 7;
; #pragma unroll
;     for (int j = 0; j < 4; ++j) { const int n = (lane >> 3) + 8 * j; const LAS float* s = scr + (8 * c) * 33 + n;
;         u32x4 o; o.x = pk2(s[0 * 33], s[1 * 33]); o.y = pk2(s[2 * 33], s[3 * 33]); o.z = pk2(s[4 * 33], s[5 * 33]); o.w = pk2(s[6 * 33], s[7 * 33]);
;         st16wt(WT, (unsigned)(((dstrow0 + n) * K + k0 + 8 * c) * 2), o); }
;     asm volatile("s_waitcnt lgkmcnt(0)" ::: "memory");
; }
.Lp1p_done1_0:
	v_mul_u32_u24_e32 v15, s14, v1
	v_add_u32_e32 v15, v15, v0
	s_mov_b32 s22, s12
	s_mov_b32 s23, s13
	s_lshl_b32 s28, s14, 1
	global_load_dword v20, v15, s[22:23] nt
	s_add_u32 s22, s22, s28
	s_addc_u32 s23, s23, 0
	global_load_dword v21, v15, s[22:23] nt
	s_add_u32 s22, s22, s28
	s_addc_u32 s23, s23, 0
	global_load_dword v22, v15, s[22:23] nt
	s_add_u32 s22, s22, s28
	s_addc_u32 s23, s23, 0
	global_load_dword v23, v15, s[22:23] nt
	s_add_u32 s22, s22, s28
	s_addc_u32 s23, s23, 0
	global_load_dword v24, v15, s[22:23] nt
	s_add_u32 s22, s22, s28
	s_addc_u32 s23, s23, 0
	global_load_dword v25, v15, s[22:23] nt
	s_add_u32 s22, s22, s28
	s_addc_u32 s23, s23, 0
	global_load_dword v26, v15, s[22:23] nt
	s_add_u32 s22, s22, s28
	s_addc_u32 s23, s23, 0
	global_load_dword v27, v15, s[22:23] nt
	s_add_u32 s22, s22, s28
	s_addc_u32 s23, s23, 0
	global_load_dword v28, v15, s[22:23] nt
	s_add_u32 s22, s22, s28
	s_addc_u32 s23, s23, 0
	global_load_dword v29, v15, s[22:23] nt
	s_add_u32 s22, s22, s28
	s_addc_u32 s23, s23, 0
	global_load_dword v30, v15, s[22:23] nt
	s_add_u32 s22, s22, s28
	s_addc_u32 s23, s23, 0
	global_load_dword v31, v15, s[22:23] nt
	s_add_u32 s22, s22, s28
	s_addc_u32 s23, s23, 0
	global_load_dword v32, v15, s[22:23] nt
	s_add_u32 s22, s22, s28
	s_addc_u32 s23, s23, 0
	global_load_dword v33, v15, s[22:23] nt
	s_add_u32 s22, s22, s28
	s_addc_u32 s23, s23, 0
	global_load_dword v34, v15, s[22:23] nt
	s_add_u32 s22, s22, s28
	s_addc_u32 s23, s23, 0
	global_load_dword v35, v15, s[22:23] nt
	s_add_u32 s22, s22, s28
	s_addc_u32 s23, s23, 0
	global_load_dword v36, v15, s[22:23] nt
	s_add_u32 s22, s22, s28
	s_addc_u32 s23, s23, 0
	global_load_dword v37, v15, s[22:23] nt
	s_add_u32 s22, s22, s28
	s_addc_u32 s23, s23, 0
	global_load_dword v38, v15, s[22:23] nt
	s_add_u32 s22, s22, s28
	s_addc_u32 s23, s23, 0
	global_load_dword v39, v15, s[22:23] nt
	s_add_u32 s22, s22, s28
	s_addc_u32 s23, s23, 0
	global_load_dword v40, v15, s[22:23] nt
	s_add_u32 s22, s22, s28
	s_addc_u32 s23, s23, 0
	global_load_dword v41, v15, s[22:23] nt
	s_add_u32 s22, s22, s28
	s_addc_u32 s23, s23, 0
	global_load_dword v42, v15, s[22:23] nt
	s_add_u32 s22, s22, s28
	s_addc_u32 s23, s23, 0
	global_load_dword v43, v15, s[22:23] nt
	s_add_u32 s22, s22, s28
	s_addc_u32 s23, s23, 0
	global_load_dword v44, v15, s[22:23] nt
	s_add_u32 s22, s22, s28
	s_addc_u32 s23, s23, 0
	global_load_dword v45, v15, s[22:23] nt
	s_add_u32 s22, s22, s28
	s_addc_u32 s23, s23, 0
	global_load_dword v46, v15, s[22:23] nt
	s_add_u32 s22, s22, s28
	s_addc_u32 s23, s23, 0
	global_load_dword v47, v15, s[22:23] nt
	s_add_u32 s22, s22, s28
	s_addc_u32 s23, s23, 0
	global_load_dword v48, v15, s[22:23] nt
	s_add_u32 s22, s22, s28
	s_addc_u32 s23, s23, 0
	global_load_dword v49, v15, s[22:23] nt
	s_add_u32 s22, s22, s28
	s_addc_u32 s23, s23, 0
	global_load_dword v50, v15, s[22:23] nt
	s_add_u32 s22, s22, s28
	s_addc_u32 s23, s23, 0
	global_load_dword v51, v15, s[22:23] nt
	s_waitcnt vmcnt(30)
	ds_write2_b32 v7, v20, v21 offset1:66
	s_waitcnt vmcnt(28)
	ds_write2_b32 v7, v22, v23 offset0:132 offset1:198
	s_waitcnt vmcnt(26)
	ds_write2_b32 v8, v24, v25 offset0:8 offset1:74
	s_waitcnt vmcnt(24)
	ds_write2_b32 v8, v26, v27 offset0:140 offset1:206
	s_waitcnt vmcnt(22)
	ds_write2_b32 v9, v28, v29 offset0:16 offset1:82
	s_waitcnt vmcnt(20)
	ds_write2_b32 v9, v30, v31 offset0:148 offset1:214
	s_waitcnt vmcnt(18)
	ds_write2_b32 v10, v32, v33 offset0:24 offset1:90
	s_waitcnt vmcnt(16)
	ds_write2_b32 v10, v34, v35 offset0:156 offset1:222
	s_waitcnt vmcnt(14)
	ds_write2_b32 v11, v36, v37 offset0:32 offset1:98
	s_waitcnt vmcnt(12)
	ds_write2_b32 v11, v38, v39 offset0:164 offset1:230
	s_waitcnt vmcnt(10)
	ds_write2_b32 v12, v40, v41 offset0:40 offset1:106
	s_waitcnt vmcnt(8)
	ds_write2_b32 v12, v42, v43 offset0:172 offset1:238
	s_waitcnt vmcnt(6)
	ds_write2_b32 v13, v44, v45 offset0:48 offset1:114
	s_waitcnt vmcnt(4)
	ds_write2_b32 v13, v46, v47 offset0:180 offset1:246
	s_waitcnt vmcnt(2)
	ds_write2_b32 v14, v48, v49 offset0:56 offset1:122
	s_waitcnt vmcnt(0)
	ds_write2_b32 v14, v50, v51 offset0:188 offset1:254
	s_waitcnt lgkmcnt(0)
	v_mul_u32_u24_e32 v148, s16, v2
	v_add3_u32 v148, v148, v3, s15
	s_lshl_b32 s29, s16, 3
	v_add_u32_e32 v149, s29, v148
	v_add_u32_e32 v150, s29, v149
	v_add_u32_e32 v151, s29, v150
	ds_read2_b32 v[100:101], v5 offset1:33
	ds_read2_b32 v[102:103], v5 offset0:66 offset1:99
	ds_read2_b32 v[104:105], v5 offset0:132 offset1:165
	ds_read2_b32 v[106:107], v5 offset0:198 offset1:231
	ds_read2_b32 v[108:109], v5 offset0:8 offset1:41
	ds_read2_b32 v[110:111], v5 offset0:74 offset1:107
	ds_read2_b32 v[112:113], v5 offset0:140 offset1:173
	ds_read2_b32 v[114:115], v5 offset0:206 offset1:239
	ds_read2_b32 v[116:117], v5 offset0:16 offset1:49
	ds_read2_b32 v[118:119], v5 offset0:82 offset1:115
	ds_read2_b32 v[120:121], v5 offset0:148 offset1:181
	ds_read2_b32 v[122:123], v5 offset0:214 offset1:247
	ds_read2_b32 v[124:125], v5 offset0:24 offset1:57
	ds_read2_b32 v[126:127], v5 offset0:90 offset1:123
	ds_read2_b32 v[128:129], v5 offset0:156 offset1:189
	ds_read2_b32 v[130:131], v5 offset0:222 offset1:255
	s_waitcnt lgkmcnt(12)
	v_cvt_pk_bf16_f32 v132, v100, v101
	v_cvt_pk_bf16_f32 v133, v102, v103
	v_cvt_pk_bf16_f32 v134, v104, v105
	v_cvt_pk_bf16_f32 v135, v106, v107
	buffer_store_dwordx4 v[132:135], v148, s[8:11], 0 offen sc1
	s_waitcnt lgkmcnt(8)
	v_cvt_pk_bf16_f32 v136, v108, v109
	v_cvt_pk_bf16_f32 v137, v110, v111
	v_cvt_pk_bf16_f32 v138, v112, v113
	v_cvt_pk_bf16_f32 v139, v114, v115
	buffer_store_dwordx4 v[136:139], v149, s[8:11], 0 offen sc1
	s_waitcnt lgkmcnt(4)
	v_cvt_pk_bf16_f32 v140, v116, v117
	v_cvt_pk_bf16_f32 v141, v118, v119
	v_cvt_pk_bf16_f32 v142, v120, v121
	v_cvt_pk_bf16_f32 v143, v122, v123
	buffer_store_dwordx4 v[140:143], v150, s[8:11], 0 offen sc1
	s_waitcnt lgkmcnt(0)
	v_cvt_pk_bf16_f32 v144, v124, v125
	v_cvt_pk_bf16_f32 v145, v126, v127
	v_cvt_pk_bf16_f32 v146, v128, v129
	v_cvt_pk_bf16_f32 v147, v130, v131
	buffer_store_dwordx4 v[144:147], v151, s[8:11], 0 offen sc1
	s_branch .LBB0_184

; #define LAS __attribute__((address_space(3)))
; __device__ __forceinline__ int wup_src(int p0) { const int j = p0 >> 8, c = p0 & 255; return (c < 128) ? 128 * j + c : DFF + 128 * j + (c - 128); }
; __device__ __forceinline__ void transpose_item(const float* W, int N, int K, bf16_t* WT, int dstrow0, int srccol0, int k0, LAS float* scr, int lane) {
;     float tv[32];
;     { const float* wp = W + (size_t)(k0 + (lane >> 5)) * N + srccol0 + (lane & 31);
; #pragma unroll
;       for (int i = 0; i < 32; ++i) tv[i] = __builtin_nontemporal_load(wp + (size_t)(2 * i) * N); }
; __device__ __forceinline__ void transposes(const Params& p, LAS unsigned char* lds, int it_begin, int it_end, int gw, int NGW, int lane, int wave) {
;     ...
;     for (int it = it_begin + gw; it < it_end; it += NGW) {
;         int r = it;
;         if (r < I_IN) { const int kb = r / 96, nb = r % 96; transpose_item(p.w_in, DIN, 1024, (bf16_t*)(p.ws + WS_WIN), 32 * nb, win_src(32 * nb), 64 * kb, scr, lane); continue; } r -= I_IN;
;         if (r < I_OUT) { const int kb = r / 32, nb = r % 32; transpose_item(p.w_out, 1024, 1024, (bf16_t*)(p.ws + WS_WOUT), 32 * nb, 32 * nb, 64 * kb, scr, lane); continue; } r -= I_OUT;
;         if (r < I_UP) { const int kb = r / 176, nb = r % 176; transpose_item(p.w_up, 2 * DFF, 1024, (bf16_t*)(p.ws + WS_WUP), 32 * nb, wup_src(32 * nb), 64 * kb, scr, lane); continue; } r -= I_UP;
;         { const int kb = r / 32, nb = r % 32; transpose_item(p.w_down, 1024, DFF, (bf16_t*)(p.ws + WS_WDOWN), 32 * nb, 32 * nb, 64 * kb, scr, lane); }
.Lp1p_done2_0:
	v_mul_u32_u24_e32 v15, s14, v1
	v_add_u32_e32 v15, v15, v0
	s_mov_b32 s22, s12
	s_mov_b32 s23, s13
	s_lshl_b32 s28, s14, 1
	global_load_dword v20, v15, s[22:23] nt
	s_add_u32 s22, s22, s28
	s_addc_u32 s23, s23, 0
	global_load_dword v21, v15, s[22:23] nt
	s_add_u32 s22, s22, s28
	s_addc_u32 s23, s23, 0
	global_load_dword v22, v15, s[22:23] nt
	s_add_u32 s22, s22, s28
	s_addc_u32 s23, s23, 0
	global_load_dword v23, v15, s[22:23] nt
	s_add_u32 s22, s22, s28
	s_addc_u32 s23, s23, 0
	global_load_dword v24, v15, s[22:23] nt
	s_add_u32 s22, s22, s28
	s_addc_u32 s23, s23, 0
	global_load_dword v25, v15, s[22:23] nt
	s_add_u32 s22, s22, s28
	s_addc_u32 s23, s23, 0
	global_load_dword v26, v15, s[22:23] nt
	s_add_u32 s22, s22, s28
	s_addc_u32 s23, s23, 0
	global_load_dword v27, v15, s[22:23] nt
	s_add_u32 s22, s22, s28
	s_addc_u32 s23, s23, 0
	global_load_dword v28, v15, s[22:23] nt
	s_add_u32 s22, s22, s28
	s_addc_u32 s23, s23, 0
	global_load_dword v29, v15, s[22:23] nt
	s_add_u32 s22, s22, s28
	s_addc_u32 s23, s23, 0
	global_load_dword v30, v15, s[22:23] nt
	s_add_u32 s22, s22, s28
	s_addc_u32 s23, s23, 0
	global_load_dword v31, v15, s[22:23] nt
	s_add_u32 s22, s22, s28
	s_addc_u32 s23, s23, 0
	global_load_dword v32, v15, s[22:23] nt
	s_add_u32 s22, s22, s28
	s_addc_u32 s23, s23, 0
	global_load_dword v33, v15, s[22:23] nt
	s_add_u32 s22, s22, s28
	s_addc_u32 s23, s23, 0
	global_load_dword v34, v15, s[22:23] nt
	s_add_u32 s22, s22, s28
	s_addc_u32 s23, s23, 0
	global_load_dword v35, v15, s[22:23] nt
	s_add_u32 s22, s22, s28
	s_addc_u32 s23, s23, 0
	global_load_dword v36, v15, s[22:23] nt
	s_add_u32 s22, s22, s28
	s_addc_u32 s23, s23, 0
	global_load_dword v37, v15, s[22:23] nt
	s_add_u32 s22, s22, s28
	s_addc_u32 s23, s23, 0
	global_load_dword v38, v15, s[22:23] nt
	s_add_u32 s22, s22, s28
	s_addc_u32 s23, s23, 0
	global_load_dword v39, v15, s[22:23] nt
	s_add_u32 s22, s22, s28
	s_addc_u32 s23, s23, 0
	global_load_dword v40, v15, s[22:23] nt
	s_add_u32 s22, s22, s28
	s_addc_u32 s23, s23, 0
	global_load_dword v41, v15, s[22:23] nt
	s_add_u32 s22, s22, s28
	s_addc_u32 s23, s23, 0
	global_load_dword v42, v15, s[22:23] nt
	s_add_u32 s22, s22, s28
	s_addc_u32 s23, s23, 0
	global_load_dword v43, v15, s[22:23] nt
	s_add_u32 s22, s22, s28
	s_addc_u32 s23, s23, 0
	global_load_dword v44, v15, s[22:23] nt
	s_add_u32 s22, s22, s28
	s_addc_u32 s23, s23, 0
	global_load_dword v45, v15, s[22:23] nt
	s_add_u32 s22, s22, s28
	s_addc_u32 s23, s23, 0
	global_load_dword v46, v15, s[22:23] nt
	s_add_u32 s22, s22, s28
	s_addc_u32 s23, s23, 0
	global_load_dword v47, v15, s[22:23] nt
	s_add_u32 s22, s22, s28
	s_addc_u32 s23, s23, 0
	global_load_dword v48, v15, s[22:23] nt
	s_add_u32 s22, s22, s28
	s_addc_u32 s23, s23, 0
	global_load_dword v49, v15, s[22:23] nt
	s_add_u32 s22, s22, s28
	s_addc_u32 s23, s23, 0
	global_load_dword v50, v15, s[22:23] nt
	s_add_u32 s22, s22, s28
	s_addc_u32 s23, s23, 0
	global_load_dword v51, v15, s[22:23] nt
	s_add_i32 s22, s4, 0x580
	s_addk_i32 s22, 0xfa00
	s_cmpk_lt_u32 s22, 0x200
	s_cbranch_scc0 .Lp1p_up2_1
	s_lshr_b32 s23, s22, 5
	s_and_b32 s28, s22, 31
	s_lshl_b32 s29, s23, 18
	s_lshl_b32 s49, s28, 7
	s_add_i32 s29, s29, s49
	s_add_u32 s17, s42, s29
	s_addc_u32 s18, s43, 0
	s_movk_i32 s19, 0x1000
	s_lshl_b32 s29, s28, 16
	s_lshl_b32 s49, s23, 7
	s_add_i32 s29, s29, s49
	s_add_i32 s20, s29, 0xc00000
	s_movk_i32 s21, 0x800
	s_branch .Lp1p_done2_1

; __device__ __forceinline__ void transpose_item(const float* W, int N, int K, bf16_t* WT, int dstrow0, int srccol0, int k0, LAS float* scr, int lane) {
;     ...
;     { const float* wp = W + (size_t)(k0 + (lane >> 5)) * N + srccol0 + (lane & 31);
; #pragma unroll
;       for (int i = 0; i < 32; ++i) tv[i] = __builtin_nontemporal_load(wp + (size_t)(2 * i) * N); }
; #pragma unroll
;     for (int i = 0; i < 32; ++i) scr[(2 * i + (lane >> 5)) * 33 + (lane & 31)] = tv[i];
;     asm volatile("s_waitcnt lgkmcnt(0)" ::: "memory");
; __device__ __forceinline__ int wup_src(int p0) { const int j = p0 >> 8, c = p0 & 255; return (c < 128) ? 128 * j + c : DFF + 128 * j + (c - 128); }
.Lp1p_c2_1:
	s_lshl_b32 s29, s29, 2
	s_mul_i32 s49, s23, 0x160000
	s_add_i32 s29, s29, s49
	s_add_u32 s17, s44, s29
	s_addc_u32 s18, s45, 0
	s_movk_i32 s19, 0x5800
	s_lshl_b32 s29, s28, 16
	s_lshl_b32 s49, s23, 7
	s_add_i32 s29, s29, s49
	s_add_i32 s20, s29, 0xe00000
	s_movk_i32 s21, 0x800
	s_branch .Lp1p_done2_1
.Lp1p_dn2_1:
	s_addk_i32 s22, 0xf500
	s_lshr_b32 s23, s22, 5
	s_and_b32 s28, s22, 31
	s_lshl_b32 s29, s23, 18
	s_lshl_b32 s49, s28, 7
	s_add_i32 s29, s29, s49
	s_add_u32 s17, s46, s29
	s_addc_u32 s18, s47, 0
	s_movk_i32 s19, 0x1000
	s_mul_i32 s29, s28, 0x2c000
	s_lshl_b32 s49, s23, 7
	s_add_i32 s29, s29, s49
	s_add_i32 s20, s29, 0x1900000
	s_movk_i32 s21, 0x1600
.Lp1p_done2_1:
	v_mul_u32_u24_e32 v16, s19, v1
	v_add_u32_e32 v16, v16, v0
	s_mov_b32 s22, s17
	s_mov_b32 s23, s18
	s_lshl_b32 s28, s19, 1
	global_load_dword v52, v16, s[22:23] nt
	s_add_u32 s22, s22, s28
	s_addc_u32 s23, s23, 0
	global_load_dword v53, v16, s[22:23] nt
	s_add_u32 s22, s22, s28
	s_addc_u32 s23, s23, 0
	global_load_dword v54, v16, s[22:23] nt
	s_add_u32 s22, s22, s28
	s_addc_u32 s23, s23, 0
	global_load_dword v55, v16, s[22:23] nt
	s_add_u32 s22, s22, s28
	s_addc_u32 s23, s23, 0
	global_load_dword v56, v16, s[22:23] nt
	s_add_u32 s22, s22, s28
	s_addc_u32 s23, s23, 0
	global_load_dword v57, v16, s[22:23] nt
	s_add_u32 s22, s22, s28
	s_addc_u32 s23, s23, 0
	global_load_dword v58, v16, s[22:23] nt
	s_add_u32 s22, s22, s28
	s_addc_u32 s23, s23, 0
	global_load_dword v59, v16, s[22:23] nt
	s_add_u32 s22, s22, s28
	s_addc_u32 s23, s23, 0
	global_load_dword v60, v16, s[22:23] nt
	s_add_u32 s22, s22, s28
	s_addc_u32 s23, s23, 0
	global_load_dword v61, v16, s[22:23] nt
	s_add_u32 s22, s22, s28
	s_addc_u32 s23, s23, 0
	global_load_dword v62, v16, s[22:23] nt
	s_add_u32 s22, s22, s28
	s_addc_u32 s23, s23, 0
	global_load_dword v63, v16, s[22:23] nt
	s_add_u32 s22, s22, s28
	s_addc_u32 s23, s23, 0
	global_load_dword v64, v16, s[22:23] nt
	s_add_u32 s22, s22, s28
	s_addc_u32 s23, s23, 0
	global_load_dword v65, v16, s[22:23] nt
	s_add_u32 s22, s22, s28
	s_addc_u32 s23, s23, 0
	global_load_dword v66, v16, s[22:23] nt
	s_add_u32 s22, s22, s28
	s_addc_u32 s23, s23, 0
	global_load_dword v67, v16, s[22:23] nt
	s_add_u32 s22, s22, s28
	s_addc_u32 s23, s23, 0
	global_load_dword v68, v16, s[22:23] nt
	s_add_u32 s22, s22, s28
	s_addc_u32 s23, s23, 0
	global_load_dword v69, v16, s[22:23] nt
	s_add_u32 s22, s22, s28
	s_addc_u32 s23, s23, 0
	global_load_dword v70, v16, s[22:23] nt
	s_add_u32 s22, s22, s28
	s_addc_u32 s23, s23, 0
	global_load_dword v71, v16, s[22:23] nt
	s_add_u32 s22, s22, s28
	s_addc_u32 s23, s23, 0
	global_load_dword v72, v16, s[22:23] nt
	s_add_u32 s22, s22, s28
	s_addc_u32 s23, s23, 0
	global_load_dword v73, v16, s[22:23] nt
	s_add_u32 s22, s22, s28
	s_addc_u32 s23, s23, 0
	global_load_dword v74, v16, s[22:23] nt
	s_add_u32 s22, s22, s28
	s_addc_u32 s23, s23, 0
	global_load_dword v75, v16, s[22:23] nt
	s_add_u32 s22, s22, s28
	s_addc_u32 s23, s23, 0
	global_load_dword v76, v16, s[22:23] nt
	s_add_u32 s22, s22, s28
	s_addc_u32 s23, s23, 0
	global_load_dword v77, v16, s[22:23] nt
	s_add_u32 s22, s22, s28
	s_addc_u32 s23, s23, 0
	global_load_dword v78, v16, s[22:23] nt
	s_add_u32 s22, s22, s28
	s_addc_u32 s23, s23, 0
	global_load_dword v79, v16, s[22:23] nt
	s_add_u32 s22, s22, s28
	s_addc_u32 s23, s23, 0
	global_load_dword v80, v16, s[22:23] nt
	s_add_u32 s22, s22, s28
	s_addc_u32 s23, s23, 0
	global_load_dword v81, v16, s[22:23] nt
	s_add_u32 s22, s22, s28
	s_addc_u32 s23, s23, 0
	global_load_dword v82, v16, s[22:23] nt
	s_add_u32 s22, s22, s28
	s_addc_u32 s23, s23, 0
	global_load_dword v83, v16, s[22:23] nt
	s_waitcnt vmcnt(62)
	ds_write2_b32 v7, v20, v21 offset1:66
	s_waitcnt vmcnt(60)
	ds_write2_b32 v7, v22, v23 offset0:132 offset1:198
	s_waitcnt vmcnt(58)
	ds_write2_b32 v8, v24, v25 offset0:8 offset1:74
	s_waitcnt vmcnt(56)
	ds_write2_b32 v8, v26, v27 offset0:140 offset1:206
	s_waitcnt vmcnt(54)
	ds_write2_b32 v9, v28, v29 offset0:16 offset1:82
	s_waitcnt vmcnt(52)
	ds_write2_b32 v9, v30, v31 offset0:148 offset1:214
	s_waitcnt vmcnt(50)
	ds_write2_b32 v10, v32, v33 offset0:24 offset1:90
	s_waitcnt vmcnt(48)
	ds_write2_b32 v10, v34, v35 offset0:156 offset1:222
	s_waitcnt vmcnt(46)
	ds_write2_b32 v11, v36, v37 offset0:32 offset1:98
	s_waitcnt vmcnt(44)
	ds_write2_b32 v11, v38, v39 offset0:164 offset1:230
	s_waitcnt vmcnt(42)
	ds_write2_b32 v12, v40, v41 offset0:40 offset1:106
	s_waitcnt vmcnt(40)
	ds_write2_b32 v12, v42, v43 offset0:172 offset1:238
	s_waitcnt vmcnt(38)
	ds_write2_b32 v13, v44, v45 offset0:48 offset1:114
	s_waitcnt vmcnt(36)
	ds_write2_b32 v13, v46, v47 offset0:180 offset1:246
	s_waitcnt vmcnt(34)
	ds_write2_b32 v14, v48, v49 offset0:56 offset1:122
	s_waitcnt vmcnt(32)
	ds_write2_b32 v14, v50, v51 offset0:188 offset1:254
	s_waitcnt lgkmcnt(0)
; #define LAS __attribute__((address_space(3)))
; __device__ __forceinline__ unsigned pk2(float lo, float hi) { return pg8::cvt_pk_bf16(lo, hi); }
; __device__ __forceinline__ void transpose_item(const float* W, int N, int K, bf16_t* WT, int dstrow0, int srccol0, int k0, LAS float* scr, int lane) {
;     ...
; #pragma unroll
;     for (int i = 0; i < 32; ++i) scr[(2 * i + (lane >> 5)) * 33 + (lane & 31)] = tv[i];
;     asm volatile("s_waitcnt lgkmcnt(0)" ::: "memory");
;     const int c = lane & 7;
; #pragma unroll
;     for (int j = 0; j < 4; ++j) { const int n = (lane >> 3) + 8 * j; const LAS float* s = scr + (8 * c) * 33 + n;
;         u32x4 o; o.x = pk2(s[0 * 33], s[1 * 33]); o.y = pk2(s[2 * 33], s[3 * 33]); o.z = pk2(s[4 * 33], s[5 * 33]); o.w = pk2(s[6 * 33], s[7 * 33]);
;         st16wt(WT, (unsigned)(((dstrow0 + n) * K + k0 + 8 * c) * 2), o); }
;     asm volatile("s_waitcnt lgkmcnt(0)" ::: "memory");
	v_mul_u32_u24_e32 v148, s16, v2
	v_add3_u32 v148, v148, v3, s15
	s_lshl_b32 s29, s16, 3
	v_add_u32_e32 v149, s29, v148
	v_add_u32_e32 v150, s29, v149
	v_add_u32_e32 v151, s29, v150
	ds_read2_b32 v[100:101], v5 offset1:33
	ds_read2_b32 v[102:103], v5 offset0:66 offset1:99
	ds_read2_b32 v[104:105], v5 offset0:132 offset1:165
	ds_read2_b32 v[106:107], v5 offset0:198 offset1:231
	ds_read2_b32 v[108:109], v5 offset0:8 offset1:41
	ds_read2_b32 v[110:111], v5 offset0:74 offset1:107
	ds_read2_b32 v[112:113], v5 offset0:140 offset1:173
	ds_read2_b32 v[114:115], v5 offset0:206 offset1:239
	ds_read2_b32 v[116:117], v5 offset0:16 offset1:49
	ds_read2_b32 v[118:119], v5 offset0:82 offset1:115
	ds_read2_b32 v[120:121], v5 offset0:148 offset1:181
	ds_read2_b32 v[122:123], v5 offset0:214 offset1:247
	ds_read2_b32 v[124:125], v5 offset0:24 offset1:57
	ds_read2_b32 v[126:127], v5 offset0:90 offset1:123
	ds_read2_b32 v[128:129], v5 offset0:156 offset1:189
	ds_read2_b32 v[130:131], v5 offset0:222 offset1:255
	s_waitcnt lgkmcnt(12)
	v_cvt_pk_bf16_f32 v132, v100, v101
	v_cvt_pk_bf16_f32 v133, v102, v103
	v_cvt_pk_bf16_f32 v134, v104, v105
	v_cvt_pk_bf16_f32 v135, v106, v107
	buffer_store_dwordx4 v[132:135], v148, s[8:11], 0 offen sc1
	s_waitcnt lgkmcnt(8)
	v_cvt_pk_bf16_f32 v136, v108, v109
	v_cvt_pk_bf16_f32 v137, v110, v111
	v_cvt_pk_bf16_f32 v138, v112, v113
	v_cvt_pk_bf16_f32 v139, v114, v115
	buffer_store_dwordx4 v[136:139], v149, s[8:11], 0 offen sc1
	s_waitcnt lgkmcnt(4)
	v_cvt_pk_bf16_f32 v140, v116, v117
	v_cvt_pk_bf16_f32 v141, v118, v119
	v_cvt_pk_bf16_f32 v142, v120, v121
	v_cvt_pk_bf16_f32 v143, v122, v123
	buffer_store_dwordx4 v[140:143], v150, s[8:11], 0 offen sc1
	s_waitcnt lgkmcnt(0)
	v_cvt_pk_bf16_f32 v144, v124, v125
	v_cvt_pk_bf16_f32 v145, v126, v127
	v_cvt_pk_bf16_f32 v146, v128, v129
	v_cvt_pk_bf16_f32 v147, v130, v131
	buffer_store_dwordx4 v[144:147], v151, s[8:11], 0 offen sc1
	s_waitcnt vmcnt(34)
	ds_write2_b32 v7, v52, v53 offset1:66
	s_waitcnt vmcnt(32)
	ds_write2_b32 v7, v54, v55 offset0:132 offset1:198
	s_waitcnt vmcnt(30)
	ds_write2_b32 v8, v56, v57 offset0:8 offset1:74
	s_waitcnt vmcnt(28)
	ds_write2_b32 v8, v58, v59 offset0:140 offset1:206
	s_waitcnt vmcnt(26)
	ds_write2_b32 v9, v60, v61 offset0:16 offset1:82
	s_waitcnt vmcnt(24)
	ds_write2_b32 v9, v62, v63 offset0:148 offset1:214
	s_waitcnt vmcnt(22)
	ds_write2_b32 v10, v64, v65 offset0:24 offset1:90
	s_waitcnt vmcnt(20)
	ds_write2_b32 v10, v66, v67 offset0:156 offset1:222
	s_waitcnt vmcnt(18)
	ds_write2_b32 v11, v68, v69 offset0:32 offset1:98
	s_waitcnt vmcnt(16)
	ds_write2_b32 v11, v70, v71 offset0:164 offset1:230
	s_waitcnt vmcnt(14)
	ds_write2_b32 v12, v72, v73 offset0:40 offset1:106
	s_waitcnt vmcnt(12)
	ds_write2_b32 v12, v74, v75 offset0:172 offset1:238
	s_waitcnt vmcnt(10)
	ds_write2_b32 v13, v76, v77 offset0:48 offset1:114
	s_waitcnt vmcnt(8)
	ds_write2_b32 v13, v78, v79 offset0:180 offset1:246
	s_waitcnt vmcnt(6)
	ds_write2_b32 v14, v80, v81 offset0:56 offset1:122
	s_waitcnt vmcnt(4)
	ds_write2_b32 v14, v82, v83 offset0:188 offset1:254
	s_waitcnt lgkmcnt(0)
	v_mul_u32_u24_e32 v148, s21, v2
	v_add3_u32 v148, v148, v3, s20
	s_lshl_b32 s29, s21, 3
	v_add_u32_e32 v149, s29, v148
	v_add_u32_e32 v150, s29, v149
	v_add_u32_e32 v151, s29, v150
	ds_read2_b32 v[100:101], v5 offset1:33
	ds_read2_b32 v[102:103], v5 offset0:66 offset1:99
	ds_read2_b32 v[104:105], v5 offset0:132 offset1:165
	ds_read2_b32 v[106:107], v5 offset0:198 offset1:231
	ds_read2_b32 v[108:109], v5 offset0:8 offset1:41
	ds_read2_b32 v[110:111], v5 offset0:74 offset1:107
	ds_read2_b32 v[112:113], v5 offset0:140 offset1:173
	ds_read2_b32 v[114:115], v5 offset0:206 offset1:239
	ds_read2_b32 v[116:117], v5 offset0:16 offset1:49
	ds_read2_b32 v[118:119], v5 offset0:82 offset1:115
	ds_read2_b32 v[120:121], v5 offset0:148 offset1:181
	ds_read2_b32 v[122:123], v5 offset0:214 offset1:247
	ds_read2_b32 v[124:125], v5 offset0:24 offset1:57
	ds_read2_b32 v[126:127], v5 offset0:90 offset1:123
	ds_read2_b32 v[128:129], v5 offset0:156 offset1:189
	ds_read2_b32 v[130:131], v5 offset0:222 offset1:255
	s_waitcnt lgkmcnt(12)
	v_cvt_pk_bf16_f32 v132, v100, v101
	v_cvt_pk_bf16_f32 v133, v102, v103
	v_cvt_pk_bf16_f32 v134, v104, v105
	v_cvt_pk_bf16_f32 v135, v106, v107
	buffer_store_dwordx4 v[132:135], v148, s[8:11], 0 offen sc1
	s_waitcnt lgkmcnt(8)
	v_cvt_pk_bf16_f32 v136, v108, v109
	v_cvt_pk_bf16_f32 v137, v110, v111
	v_cvt_pk_bf16_f32 v138, v112, v113
	v_cvt_pk_bf16_f32 v139, v114, v115
	buffer_store_dwordx4 v[136:139], v149, s[8:11], 0 offen sc1
	s_waitcnt lgkmcnt(4)
	v_cvt_pk_bf16_f32 v140, v116, v117
	v_cvt_pk_bf16_f32 v141, v118, v119
	v_cvt_pk_bf16_f32 v142, v120, v121
	v_cvt_pk_bf16_f32 v143, v122, v123
	buffer_store_dwordx4 v[140:143], v150, s[8:11], 0 offen sc1
	s_waitcnt lgkmcnt(0)
	v_cvt_pk_bf16_f32 v144, v124, v125
	v_cvt_pk_bf16_f32 v145, v126, v127
	v_cvt_pk_bf16_f32 v146, v128, v129
	v_cvt_pk_bf16_f32 v147, v130, v131
	buffer_store_dwordx4 v[144:147], v151, s[8:11], 0 offen sc1
	s_branch .LBB0_184

; #define LAS __attribute__((address_space(3)))
; __device__ __forceinline__ int wup_src(int p0) { const int j = p0 >> 8, c = p0 & 255; return (c < 128) ? 128 * j + c : DFF + 128 * j + (c - 128); }
; __device__ __forceinline__ void transpose_item(const float* W, int N, int K, bf16_t* WT, int dstrow0, int srccol0, int k0, LAS float* scr, int lane) {
;     float tv[32];
;     { const float* wp = W + (size_t)(k0 + (lane >> 5)) * N + srccol0 + (lane & 31);
; #pragma unroll
;       for (int i = 0; i < 32; ++i) tv[i] = __builtin_nontemporal_load(wp + (size_t)(2 * i) * N); }
; __device__ __forceinline__ void transposes(const Params& p, LAS unsigned char* lds, int it_begin, int it_end, int gw, int NGW, int lane, int wave) {
;     ...
;     for (int it = it_begin + gw; it < it_end; it += NGW) {
;         int r = it;
;         if (r < I_IN) { const int kb = r / 96, nb = r % 96; transpose_item(p.w_in, DIN, 1024, (bf16_t*)(p.ws + WS_WIN), 32 * nb, win_src(32 * nb), 64 * kb, scr, lane); continue; } r -= I_IN;
;         if (r < I_OUT) { const int kb = r / 32, nb = r % 32; transpose_item(p.w_out, 1024, 1024, (bf16_t*)(p.ws + WS_WOUT), 32 * nb, 32 * nb, 64 * kb, scr, lane); continue; } r -= I_OUT;
;         if (r < I_UP) { const int kb = r / 176, nb = r % 176; transpose_item(p.w_up, 2 * DFF, 1024, (bf16_t*)(p.ws + WS_WUP), 32 * nb, wup_src(32 * nb), 64 * kb, scr, lane); continue; } r -= I_UP;
;         { const int kb = r / 32, nb = r % 32; transpose_item(p.w_down, 1024, DFF, (bf16_t*)(p.ws + WS_WDOWN), 32 * nb, 32 * nb, 64 * kb, scr, lane); }
.Lp1p_done3_0:
	v_mul_u32_u24_e32 v15, s14, v1
	v_add_u32_e32 v15, v15, v0
	s_mov_b32 s22, s12
	s_mov_b32 s23, s13
	s_lshl_b32 s28, s14, 1
	global_load_dword v20, v15, s[22:23] nt
	s_add_u32 s22, s22, s28
	s_addc_u32 s23, s23, 0
	global_load_dword v21, v15, s[22:23] nt
	s_add_u32 s22, s22, s28
	s_addc_u32 s23, s23, 0
	global_load_dword v22, v15, s[22:23] nt
	s_add_u32 s22, s22, s28
	s_addc_u32 s23, s23, 0
	global_load_dword v23, v15, s[22:23] nt
	s_add_u32 s22, s22, s28
	s_addc_u32 s23, s23, 0
	global_load_dword v24, v15, s[22:23] nt
	s_add_u32 s22, s22, s28
	s_addc_u32 s23, s23, 0
	global_load_dword v25, v15, s[22:23] nt
	s_add_u32 s22, s22, s28
	s_addc_u32 s23, s23, 0
	global_load_dword v26, v15, s[22:23] nt
	s_add_u32 s22, s22, s28
	s_addc_u32 s23, s23, 0
	global_load_dword v27, v15, s[22:23] nt
	s_add_u32 s22, s22, s28
	s_addc_u32 s23, s23, 0
	global_load_dword v28, v15, s[22:23] nt
	s_add_u32 s22, s22, s28
	s_addc_u32 s23, s23, 0
	global_load_dword v29, v15, s[22:23] nt
	s_add_u32 s22, s22, s28
	s_addc_u32 s23, s23, 0
	global_load_dword v30, v15, s[22:23] nt
	s_add_u32 s22, s22, s28
	s_addc_u32 s23, s23, 0
	global_load_dword v31, v15, s[22:23] nt
	s_add_u32 s22, s22, s28
	s_addc_u32 s23, s23, 0
	global_load_dword v32, v15, s[22:23] nt
	s_add_u32 s22, s22, s28
	s_addc_u32 s23, s23, 0
	global_load_dword v33, v15, s[22:23] nt
	s_add_u32 s22, s22, s28
	s_addc_u32 s23, s23, 0
	global_load_dword v34, v15, s[22:23] nt
	s_add_u32 s22, s22, s28
	s_addc_u32 s23, s23, 0
	global_load_dword v35, v15, s[22:23] nt
	s_add_u32 s22, s22, s28
	s_addc_u32 s23, s23, 0
	global_load_dword v36, v15, s[22:23] nt
	s_add_u32 s22, s22, s28
	s_addc_u32 s23, s23, 0
	global_load_dword v37, v15, s[22:23] nt
	s_add_u32 s22, s22, s28
	s_addc_u32 s23, s23, 0
	global_load_dword v38, v15, s[22:23] nt
	s_add_u32 s22, s22, s28
	s_addc_u32 s23, s23, 0
	global_load_dword v39, v15, s[22:23] nt
	s_add_u32 s22, s22, s28
	s_addc_u32 s23, s23, 0
	global_load_dword v40, v15, s[22:23] nt
	s_add_u32 s22, s22, s28
	s_addc_u32 s23, s23, 0
	global_load_dword v41, v15, s[22:23] nt
	s_add_u32 s22, s22, s28
	s_addc_u32 s23, s23, 0
	global_load_dword v42, v15, s[22:23] nt
	s_add_u32 s22, s22, s28
	s_addc_u32 s23, s23, 0
	global_load_dword v43, v15, s[22:23] nt
	s_add_u32 s22, s22, s28
	s_addc_u32 s23, s23, 0
	global_load_dword v44, v15, s[22:23] nt
	s_add_u32 s22, s22, s28
	s_addc_u32 s23, s23, 0
	global_load_dword v45, v15, s[22:23] nt
	s_add_u32 s22, s22, s28
	s_addc_u32 s23, s23, 0
	global_load_dword v46, v15, s[22:23] nt
	s_add_u32 s22, s22, s28
	s_addc_u32 s23, s23, 0
	global_load_dword v47, v15, s[22:23] nt
	s_add_u32 s22, s22, s28
	s_addc_u32 s23, s23, 0
	global_load_dword v48, v15, s[22:23] nt
	s_add_u32 s22, s22, s28
	s_addc_u32 s23, s23, 0
	global_load_dword v49, v15, s[22:23] nt
	s_add_u32 s22, s22, s28
	s_addc_u32 s23, s23, 0
	global_load_dword v50, v15, s[22:23] nt
	s_add_u32 s22, s22, s28
	s_addc_u32 s23, s23, 0
	global_load_dword v51, v15, s[22:23] nt
	s_add_i32 s22, s4, 0x280
	s_addk_i32 s22, 0xfa00
	s_cmpk_lt_u32 s22, 0x200
	s_cbranch_scc0 .Lp1p_up3_1
	s_lshr_b32 s23, s22, 5
	s_and_b32 s28, s22, 31
	s_lshl_b32 s29, s23, 18
	s_lshl_b32 s49, s28, 7
	s_add_i32 s29, s29, s49
	s_add_u32 s17, s42, s29
	s_addc_u32 s18, s43, 0
	s_movk_i32 s19, 0x1000
	s_lshl_b32 s29, s28, 16
	s_lshl_b32 s49, s23, 7
	s_add_i32 s29, s29, s49
	s_add_i32 s20, s29, 0xc00000
	s_movk_i32 s21, 0x800
	s_branch .Lp1p_done3_1

; __device__ __forceinline__ int wup_src(int p0) { const int j = p0 >> 8, c = p0 & 255; return (c < 128) ? 128 * j + c : DFF + 128 * j + (c - 128); }
; __device__ __forceinline__ void transpose_item(const float* W, int N, int K, bf16_t* WT, int dstrow0, int srccol0, int k0, LAS float* scr, int lane) {
;     ...
;     { const float* wp = W + (size_t)(k0 + (lane >> 5)) * N + srccol0 + (lane & 31);
; #pragma unroll
;       for (int i = 0; i < 32; ++i) tv[i] = __builtin_nontemporal_load(wp + (size_t)(2 * i) * N); }
; #pragma unroll
;     for (int i = 0; i < 32; ++i) scr[(2 * i + (lane >> 5)) * 33 + (lane & 31)] = tv[i];
;     asm volatile("s_waitcnt lgkmcnt(0)" ::: "memory");
; __device__ __forceinline__ void transposes(const Params& p, LAS unsigned char* lds, int it_begin, int it_end, int gw, int NGW, int lane, int wave) {
;     ...
;     for (int it = it_begin + gw; it < it_end; it += NGW) {
;         int r = it;
;         if (r < I_IN) { const int kb = r / 96, nb = r % 96; transpose_item(p.w_in, DIN, 1024, (bf16_t*)(p.ws + WS_WIN), 32 * nb, win_src(32 * nb), 64 * kb, scr, lane); continue; } r -= I_IN;
;         if (r < I_OUT) { const int kb = r / 32, nb = r % 32; transpose_item(p.w_out, 1024, 1024, (bf16_t*)(p.ws + WS_WOUT), 32 * nb, 32 * nb, 64 * kb, scr, lane); continue; } r -= I_OUT;
;         if (r < I_UP) { const int kb = r / 176, nb = r % 176; transpose_item(p.w_up, 2 * DFF, 1024, (bf16_t*)(p.ws + WS_WUP), 32 * nb, wup_src(32 * nb), 64 * kb, scr, lane); continue; } r -= I_UP;
;         { const int kb = r / 32, nb = r % 32; transpose_item(p.w_down, 1024, DFF, (bf16_t*)(p.ws + WS_WDOWN), 32 * nb, 32 * nb, 64 * kb, scr, lane); }
.Lp1p_done3_1:
	v_mul_u32_u24_e32 v16, s19, v1
	v_add_u32_e32 v16, v16, v0
	s_mov_b32 s22, s17
	s_mov_b32 s23, s18
	s_lshl_b32 s28, s19, 1
	global_load_dword v52, v16, s[22:23] nt
	s_add_u32 s22, s22, s28
	s_addc_u32 s23, s23, 0
	global_load_dword v53, v16, s[22:23] nt
	s_add_u32 s22, s22, s28
	s_addc_u32 s23, s23, 0
	global_load_dword v54, v16, s[22:23] nt
	s_add_u32 s22, s22, s28
	s_addc_u32 s23, s23, 0
	global_load_dword v55, v16, s[22:23] nt
	s_add_u32 s22, s22, s28
	s_addc_u32 s23, s23, 0
	global_load_dword v56, v16, s[22:23] nt
	s_add_u32 s22, s22, s28
	s_addc_u32 s23, s23, 0
	global_load_dword v57, v16, s[22:23] nt
	s_add_u32 s22, s22, s28
	s_addc_u32 s23, s23, 0
	global_load_dword v58, v16, s[22:23] nt
	s_add_u32 s22, s22, s28
	s_addc_u32 s23, s23, 0
	global_load_dword v59, v16, s[22:23] nt
	s_add_u32 s22, s22, s28
	s_addc_u32 s23, s23, 0
	global_load_dword v60, v16, s[22:23] nt
	s_add_u32 s22, s22, s28
	s_addc_u32 s23, s23, 0
	global_load_dword v61, v16, s[22:23] nt
	s_add_u32 s22, s22, s28
	s_addc_u32 s23, s23, 0
	global_load_dword v62, v16, s[22:23] nt
	s_add_u32 s22, s22, s28
	s_addc_u32 s23, s23, 0
	global_load_dword v63, v16, s[22:23] nt
	s_add_u32 s22, s22, s28
	s_addc_u32 s23, s23, 0
	global_load_dword v64, v16, s[22:23] nt
	s_add_u32 s22, s22, s28
	s_addc_u32 s23, s23, 0
	global_load_dword v65, v16, s[22:23] nt
	s_add_u32 s22, s22, s28
	s_addc_u32 s23, s23, 0
	global_load_dword v66, v16, s[22:23] nt
	s_add_u32 s22, s22, s28
	s_addc_u32 s23, s23, 0
	global_load_dword v67, v16, s[22:23] nt
	s_add_u32 s22, s22, s28
	s_addc_u32 s23, s23, 0
	global_load_dword v68, v16, s[22:23] nt
	s_add_u32 s22, s22, s28
	s_addc_u32 s23, s23, 0
	global_load_dword v69, v16, s[22:23] nt
	s_add_u32 s22, s22, s28
	s_addc_u32 s23, s23, 0
	global_load_dword v70, v16, s[22:23] nt
	s_add_u32 s22, s22, s28
	s_addc_u32 s23, s23, 0
	global_load_dword v71, v16, s[22:23] nt
	s_add_u32 s22, s22, s28
	s_addc_u32 s23, s23, 0
	global_load_dword v72, v16, s[22:23] nt
	s_add_u32 s22, s22, s28
	s_addc_u32 s23, s23, 0
	global_load_dword v73, v16, s[22:23] nt
	s_add_u32 s22, s22, s28
	s_addc_u32 s23, s23, 0
	global_load_dword v74, v16, s[22:23] nt
	s_add_u32 s22, s22, s28
	s_addc_u32 s23, s23, 0
	global_load_dword v75, v16, s[22:23] nt
	s_add_u32 s22, s22, s28
	s_addc_u32 s23, s23, 0
	global_load_dword v76, v16, s[22:23] nt
	s_add_u32 s22, s22, s28
	s_addc_u32 s23, s23, 0
	global_load_dword v77, v16, s[22:23] nt
	s_add_u32 s22, s22, s28
	s_addc_u32 s23, s23, 0
	global_load_dword v78, v16, s[22:23] nt
	s_add_u32 s22, s22, s28
	s_addc_u32 s23, s23, 0
	global_load_dword v79, v16, s[22:23] nt
	s_add_u32 s22, s22, s28
	s_addc_u32 s23, s23, 0
	global_load_dword v80, v16, s[22:23] nt
	s_add_u32 s22, s22, s28
	s_addc_u32 s23, s23, 0
	global_load_dword v81, v16, s[22:23] nt
	s_add_u32 s22, s22, s28
	s_addc_u32 s23, s23, 0
	global_load_dword v82, v16, s[22:23] nt
	s_add_u32 s22, s22, s28
	s_addc_u32 s23, s23, 0
	global_load_dword v83, v16, s[22:23] nt
	s_waitcnt vmcnt(62)
	ds_write2_b32 v7, v20, v21 offset1:66
	s_waitcnt vmcnt(60)
	ds_write2_b32 v7, v22, v23 offset0:132 offset1:198
	s_waitcnt vmcnt(58)
	ds_write2_b32 v8, v24, v25 offset0:8 offset1:74
	s_waitcnt vmcnt(56)
	ds_write2_b32 v8, v26, v27 offset0:140 offset1:206
	s_waitcnt vmcnt(54)
	ds_write2_b32 v9, v28, v29 offset0:16 offset1:82
	s_waitcnt vmcnt(52)
	ds_write2_b32 v9, v30, v31 offset0:148 offset1:214
	s_waitcnt vmcnt(50)
	ds_write2_b32 v10, v32, v33 offset0:24 offset1:90
	s_waitcnt vmcnt(48)
	ds_write2_b32 v10, v34, v35 offset0:156 offset1:222
	s_waitcnt vmcnt(46)
	ds_write2_b32 v11, v36, v37 offset0:32 offset1:98
	s_waitcnt vmcnt(44)
	ds_write2_b32 v11, v38, v39 offset0:164 offset1:230
	s_waitcnt vmcnt(42)
	ds_write2_b32 v12, v40, v41 offset0:40 offset1:106
	s_waitcnt vmcnt(40)
	ds_write2_b32 v12, v42, v43 offset0:172 offset1:238
	s_waitcnt vmcnt(38)
	ds_write2_b32 v13, v44, v45 offset0:48 offset1:114
	s_waitcnt vmcnt(36)
	ds_write2_b32 v13, v46, v47 offset0:180 offset1:246
	s_waitcnt vmcnt(34)
	ds_write2_b32 v14, v48, v49 offset0:56 offset1:122
	s_waitcnt vmcnt(32)
	ds_write2_b32 v14, v50, v51 offset0:188 offset1:254
	s_waitcnt lgkmcnt(0)
	v_mul_u32_u24_e32 v148, s16, v2
	v_add3_u32 v148, v148, v3, s15
	s_lshl_b32 s29, s16, 3
	v_add_u32_e32 v149, s29, v148
	v_add_u32_e32 v150, s29, v149
	v_add_u32_e32 v151, s29, v150
	s_add_i32 s22, s4, 0x500
	s_addk_i32 s22, 0xfa00
	s_cmpk_lt_u32 s22, 0x200
	s_cbranch_scc0 .Lp1p_up3_2
	s_lshr_b32 s23, s22, 5
	s_and_b32 s28, s22, 31
	s_lshl_b32 s29, s23, 18
	s_lshl_b32 s49, s28, 7
	s_add_i32 s29, s29, s49
	s_add_u32 s12, s42, s29
	s_addc_u32 s13, s43, 0
	s_movk_i32 s14, 0x1000
	s_lshl_b32 s29, s28, 16
	s_lshl_b32 s49, s23, 7
	s_add_i32 s29, s29, s49
	s_add_i32 s15, s29, 0xc00000
	s_movk_i32 s16, 0x800
	s_branch .Lp1p_done3_2

; #define LAS __attribute__((address_space(3)))
; __device__ __forceinline__ unsigned pk2(float lo, float hi) { return pg8::cvt_pk_bf16(lo, hi); }
; __device__ __forceinline__ void transpose_item(const float* W, int N, int K, bf16_t* WT, int dstrow0, int srccol0, int k0, LAS float* scr, int lane) {
;     ...
;     { const float* wp = W + (size_t)(k0 + (lane >> 5)) * N + srccol0 + (lane & 31);
; #pragma unroll
;       for (int i = 0; i < 32; ++i) tv[i] = __builtin_nontemporal_load(wp + (size_t)(2 * i) * N); }
; #pragma unroll
;     for (int i = 0; i < 32; ++i) scr[(2 * i + (lane >> 5)) * 33 + (lane & 31)] = tv[i];
;     asm volatile("s_waitcnt lgkmcnt(0)" ::: "memory");
;     const int c = lane & 7;
; #pragma unroll
;     for (int j = 0; j < 4; ++j) { const int n = (lane >> 3) + 8 * j; const LAS float* s = scr + (8 * c) * 33 + n;
;         u32x4 o; o.x = pk2(s[0 * 33], s[1 * 33]); o.y = pk2(s[2 * 33], s[3 * 33]); o.z = pk2(s[4 * 33], s[5 * 33]); o.w = pk2(s[6 * 33], s[7 * 33]);
;         st16wt(WT, (unsigned)(((dstrow0 + n) * K + k0 + 8 * c) * 2), o); }
;     asm volatile("s_waitcnt lgkmcnt(0)" ::: "memory");
.Lp1p_done3_2:
	v_mul_u32_u24_e32 v15, s14, v1
	v_add_u32_e32 v15, v15, v0
	s_mov_b32 s22, s12
	s_mov_b32 s23, s13
	s_lshl_b32 s28, s14, 1
	global_load_dword v20, v15, s[22:23] nt
	s_add_u32 s22, s22, s28
	s_addc_u32 s23, s23, 0
	global_load_dword v21, v15, s[22:23] nt
	s_add_u32 s22, s22, s28
	s_addc_u32 s23, s23, 0
	global_load_dword v22, v15, s[22:23] nt
	s_add_u32 s22, s22, s28
	s_addc_u32 s23, s23, 0
	global_load_dword v23, v15, s[22:23] nt
	s_add_u32 s22, s22, s28
	s_addc_u32 s23, s23, 0
	global_load_dword v24, v15, s[22:23] nt
	s_add_u32 s22, s22, s28
	s_addc_u32 s23, s23, 0
	global_load_dword v25, v15, s[22:23] nt
	s_add_u32 s22, s22, s28
	s_addc_u32 s23, s23, 0
	global_load_dword v26, v15, s[22:23] nt
	s_add_u32 s22, s22, s28
	s_addc_u32 s23, s23, 0
	global_load_dword v27, v15, s[22:23] nt
	s_add_u32 s22, s22, s28
	s_addc_u32 s23, s23, 0
	global_load_dword v28, v15, s[22:23] nt
	s_add_u32 s22, s22, s28
	s_addc_u32 s23, s23, 0
	global_load_dword v29, v15, s[22:23] nt
	s_add_u32 s22, s22, s28
	s_addc_u32 s23, s23, 0
	global_load_dword v30, v15, s[22:23] nt
	s_add_u32 s22, s22, s28
	s_addc_u32 s23, s23, 0
	global_load_dword v31, v15, s[22:23] nt
	s_add_u32 s22, s22, s28
	s_addc_u32 s23, s23, 0
	global_load_dword v32, v15, s[22:23] nt
	s_add_u32 s22, s22, s28
	s_addc_u32 s23, s23, 0
	global_load_dword v33, v15, s[22:23] nt
	s_add_u32 s22, s22, s28
	s_addc_u32 s23, s23, 0
	global_load_dword v34, v15, s[22:23] nt
	s_add_u32 s22, s22, s28
	s_addc_u32 s23, s23, 0
	global_load_dword v35, v15, s[22:23] nt
	s_add_u32 s22, s22, s28
	s_addc_u32 s23, s23, 0
	global_load_dword v36, v15, s[22:23] nt
	s_add_u32 s22, s22, s28
	s_addc_u32 s23, s23, 0
	global_load_dword v37, v15, s[22:23] nt
	s_add_u32 s22, s22, s28
	s_addc_u32 s23, s23, 0
	global_load_dword v38, v15, s[22:23] nt
	s_add_u32 s22, s22, s28
	s_addc_u32 s23, s23, 0
	global_load_dword v39, v15, s[22:23] nt
	s_add_u32 s22, s22, s28
	s_addc_u32 s23, s23, 0
	global_load_dword v40, v15, s[22:23] nt
	s_add_u32 s22, s22, s28
	s_addc_u32 s23, s23, 0
	global_load_dword v41, v15, s[22:23] nt
	s_add_u32 s22, s22, s28
	s_addc_u32 s23, s23, 0
	global_load_dword v42, v15, s[22:23] nt
	s_add_u32 s22, s22, s28
	s_addc_u32 s23, s23, 0
	global_load_dword v43, v15, s[22:23] nt
	s_add_u32 s22, s22, s28
	s_addc_u32 s23, s23, 0
	global_load_dword v44, v15, s[22:23] nt
	s_add_u32 s22, s22, s28
	s_addc_u32 s23, s23, 0
	global_load_dword v45, v15, s[22:23] nt
	s_add_u32 s22, s22, s28
	s_addc_u32 s23, s23, 0
	global_load_dword v46, v15, s[22:23] nt
	s_add_u32 s22, s22, s28
	s_addc_u32 s23, s23, 0
	global_load_dword v47, v15, s[22:23] nt
	s_add_u32 s22, s22, s28
	s_addc_u32 s23, s23, 0
	global_load_dword v48, v15, s[22:23] nt
	s_add_u32 s22, s22, s28
	s_addc_u32 s23, s23, 0
	global_load_dword v49, v15, s[22:23] nt
	s_add_u32 s22, s22, s28
	s_addc_u32 s23, s23, 0
	global_load_dword v50, v15, s[22:23] nt
	s_add_u32 s22, s22, s28
	s_addc_u32 s23, s23, 0
	global_load_dword v51, v15, s[22:23] nt
	ds_read2_b32 v[100:101], v5 offset1:33
	ds_read2_b32 v[102:103], v5 offset0:66 offset1:99
	ds_read2_b32 v[104:105], v5 offset0:132 offset1:165
	ds_read2_b32 v[106:107], v5 offset0:198 offset1:231
	ds_read2_b32 v[108:109], v5 offset0:8 offset1:41
	ds_read2_b32 v[110:111], v5 offset0:74 offset1:107
	ds_read2_b32 v[112:113], v5 offset0:140 offset1:173
	ds_read2_b32 v[114:115], v5 offset0:206 offset1:239
	ds_read2_b32 v[116:117], v5 offset0:16 offset1:49
	ds_read2_b32 v[118:119], v5 offset0:82 offset1:115
	ds_read2_b32 v[120:121], v5 offset0:148 offset1:181
	ds_read2_b32 v[122:123], v5 offset0:214 offset1:247
	ds_read2_b32 v[124:125], v5 offset0:24 offset1:57
	ds_read2_b32 v[126:127], v5 offset0:90 offset1:123
	ds_read2_b32 v[128:129], v5 offset0:156 offset1:189
	ds_read2_b32 v[130:131], v5 offset0:222 offset1:255
	s_waitcnt lgkmcnt(12)
	v_cvt_pk_bf16_f32 v132, v100, v101
	v_cvt_pk_bf16_f32 v133, v102, v103
	v_cvt_pk_bf16_f32 v134, v104, v105
	v_cvt_pk_bf16_f32 v135, v106, v107
	buffer_store_dwordx4 v[132:135], v148, s[8:11], 0 offen sc1
	s_waitcnt lgkmcnt(8)
	v_cvt_pk_bf16_f32 v136, v108, v109
	v_cvt_pk_bf16_f32 v137, v110, v111
	v_cvt_pk_bf16_f32 v138, v112, v113
	v_cvt_pk_bf16_f32 v139, v114, v115
	buffer_store_dwordx4 v[136:139], v149, s[8:11], 0 offen sc1
	s_waitcnt lgkmcnt(4)
	v_cvt_pk_bf16_f32 v140, v116, v117
	v_cvt_pk_bf16_f32 v141, v118, v119
	v_cvt_pk_bf16_f32 v142, v120, v121
	v_cvt_pk_bf16_f32 v143, v122, v123
	buffer_store_dwordx4 v[140:143], v150, s[8:11], 0 offen sc1
	s_waitcnt lgkmcnt(0)
	v_cvt_pk_bf16_f32 v144, v124, v125
	v_cvt_pk_bf16_f32 v145, v126, v127
	v_cvt_pk_bf16_f32 v146, v128, v129
	v_cvt_pk_bf16_f32 v147, v130, v131
	buffer_store_dwordx4 v[144:147], v151, s[8:11], 0 offen sc1
	s_waitcnt vmcnt(63)
	ds_write2_b32 v7, v52, v53 offset1:66
	s_waitcnt vmcnt(63)
	ds_write2_b32 v7, v54, v55 offset0:132 offset1:198
	s_waitcnt vmcnt(62)
	ds_write2_b32 v8, v56, v57 offset0:8 offset1:74
	s_waitcnt vmcnt(60)
	ds_write2_b32 v8, v58, v59 offset0:140 offset1:206
	s_waitcnt vmcnt(58)
	ds_write2_b32 v9, v60, v61 offset0:16 offset1:82
	s_waitcnt vmcnt(56)
	ds_write2_b32 v9, v62, v63 offset0:148 offset1:214
	s_waitcnt vmcnt(54)
	ds_write2_b32 v10, v64, v65 offset0:24 offset1:90
	s_waitcnt vmcnt(52)
	ds_write2_b32 v10, v66, v67 offset0:156 offset1:222
	s_waitcnt vmcnt(50)
	ds_write2_b32 v11, v68, v69 offset0:32 offset1:98
	s_waitcnt vmcnt(48)
	ds_write2_b32 v11, v70, v71 offset0:164 offset1:230
	s_waitcnt vmcnt(46)
; #define LAS __attribute__((address_space(3)))
; __device__ __forceinline__ unsigned pk2(float lo, float hi) { return pg8::cvt_pk_bf16(lo, hi); }
; __device__ __forceinline__ void transpose_item(const float* W, int N, int K, bf16_t* WT, int dstrow0, int srccol0, int k0, LAS float* scr, int lane) {
;     ...
; #pragma unroll
;     for (int i = 0; i < 32; ++i) scr[(2 * i + (lane >> 5)) * 33 + (lane & 31)] = tv[i];
;     asm volatile("s_waitcnt lgkmcnt(0)" ::: "memory");
;     const int c = lane & 7;
; #pragma unroll
;     for (int j = 0; j < 4; ++j) { const int n = (lane >> 3) + 8 * j; const LAS float* s = scr + (8 * c) * 33 + n;
;         u32x4 o; o.x = pk2(s[0 * 33], s[1 * 33]); o.y = pk2(s[2 * 33], s[3 * 33]); o.z = pk2(s[4 * 33], s[5 * 33]); o.w = pk2(s[6 * 33], s[7 * 33]);
;         st16wt(WT, (unsigned)(((dstrow0 + n) * K + k0 + 8 * c) * 2), o); }
;     asm volatile("s_waitcnt lgkmcnt(0)" ::: "memory");
	ds_write2_b32 v12, v72, v73 offset0:40 offset1:106
	s_waitcnt vmcnt(44)
	ds_write2_b32 v12, v74, v75 offset0:172 offset1:238
	s_waitcnt vmcnt(42)
	ds_write2_b32 v13, v76, v77 offset0:48 offset1:114
	s_waitcnt vmcnt(40)
	ds_write2_b32 v13, v78, v79 offset0:180 offset1:246
	s_waitcnt vmcnt(38)
	ds_write2_b32 v14, v80, v81 offset0:56 offset1:122
	s_waitcnt vmcnt(36)
	ds_write2_b32 v14, v82, v83 offset0:188 offset1:254
	s_waitcnt lgkmcnt(0)
	v_mul_u32_u24_e32 v148, s21, v2
	v_add3_u32 v148, v148, v3, s20
	s_lshl_b32 s29, s21, 3
	v_add_u32_e32 v149, s29, v148
	v_add_u32_e32 v150, s29, v149
	v_add_u32_e32 v151, s29, v150
	ds_read2_b32 v[100:101], v5 offset1:33
	ds_read2_b32 v[102:103], v5 offset0:66 offset1:99
	ds_read2_b32 v[104:105], v5 offset0:132 offset1:165
	ds_read2_b32 v[106:107], v5 offset0:198 offset1:231
	ds_read2_b32 v[108:109], v5 offset0:8 offset1:41
	ds_read2_b32 v[110:111], v5 offset0:74 offset1:107
	ds_read2_b32 v[112:113], v5 offset0:140 offset1:173
	ds_read2_b32 v[114:115], v5 offset0:206 offset1:239
	ds_read2_b32 v[116:117], v5 offset0:16 offset1:49
	ds_read2_b32 v[118:119], v5 offset0:82 offset1:115
	ds_read2_b32 v[120:121], v5 offset0:148 offset1:181
	ds_read2_b32 v[122:123], v5 offset0:214 offset1:247
	ds_read2_b32 v[124:125], v5 offset0:24 offset1:57
	ds_read2_b32 v[126:127], v5 offset0:90 offset1:123
	ds_read2_b32 v[128:129], v5 offset0:156 offset1:189
	ds_read2_b32 v[130:131], v5 offset0:222 offset1:255
	s_waitcnt lgkmcnt(12)
	v_cvt_pk_bf16_f32 v132, v100, v101
	v_cvt_pk_bf16_f32 v133, v102, v103
	v_cvt_pk_bf16_f32 v134, v104, v105
	v_cvt_pk_bf16_f32 v135, v106, v107
	buffer_store_dwordx4 v[132:135], v148, s[8:11], 0 offen sc1
	s_waitcnt lgkmcnt(8)
	v_cvt_pk_bf16_f32 v136, v108, v109
	v_cvt_pk_bf16_f32 v137, v110, v111
	v_cvt_pk_bf16_f32 v138, v112, v113
	v_cvt_pk_bf16_f32 v139, v114, v115
	buffer_store_dwordx4 v[136:139], v149, s[8:11], 0 offen sc1
	s_waitcnt lgkmcnt(4)
	v_cvt_pk_bf16_f32 v140, v116, v117
	v_cvt_pk_bf16_f32 v141, v118, v119
	v_cvt_pk_bf16_f32 v142, v120, v121
	v_cvt_pk_bf16_f32 v143, v122, v123
	buffer_store_dwordx4 v[140:143], v150, s[8:11], 0 offen sc1
	s_waitcnt lgkmcnt(0)
	v_cvt_pk_bf16_f32 v144, v124, v125
	v_cvt_pk_bf16_f32 v145, v126, v127
	v_cvt_pk_bf16_f32 v146, v128, v129
	v_cvt_pk_bf16_f32 v147, v130, v131
	buffer_store_dwordx4 v[144:147], v151, s[8:11], 0 offen sc1
	s_waitcnt vmcnt(38)
	ds_write2_b32 v7, v20, v21 offset1:66
	s_waitcnt vmcnt(36)
	ds_write2_b32 v7, v22, v23 offset0:132 offset1:198
	s_waitcnt vmcnt(34)
	ds_write2_b32 v8, v24, v25 offset0:8 offset1:74
	s_waitcnt vmcnt(32)
	ds_write2_b32 v8, v26, v27 offset0:140 offset1:206
	s_waitcnt vmcnt(30)
	ds_write2_b32 v9, v28, v29 offset0:16 offset1:82
	s_waitcnt vmcnt(28)
	ds_write2_b32 v9, v30, v31 offset0:148 offset1:214
	s_waitcnt vmcnt(26)
	ds_write2_b32 v10, v32, v33 offset0:24 offset1:90
	s_waitcnt vmcnt(24)
	ds_write2_b32 v10, v34, v35 offset0:156 offset1:222
	s_waitcnt vmcnt(22)
	ds_write2_b32 v11, v36, v37 offset0:32 offset1:98
	s_waitcnt vmcnt(20)
	ds_write2_b32 v11, v38, v39 offset0:164 offset1:230
	s_waitcnt vmcnt(18)
	ds_write2_b32 v12, v40, v41 offset0:40 offset1:106
	s_waitcnt vmcnt(16)
	ds_write2_b32 v12, v42, v43 offset0:172 offset1:238
	s_waitcnt vmcnt(14)
	ds_write2_b32 v13, v44, v45 offset0:48 offset1:114
	s_waitcnt vmcnt(12)
	ds_write2_b32 v13, v46, v47 offset0:180 offset1:246
	s_waitcnt vmcnt(10)
	ds_write2_b32 v14, v48, v49 offset0:56 offset1:122
	s_waitcnt vmcnt(8)
	ds_write2_b32 v14, v50, v51 offset0:188 offset1:254
	s_waitcnt lgkmcnt(0)
	v_mul_u32_u24_e32 v148, s16, v2
	v_add3_u32 v148, v148, v3, s15
	s_lshl_b32 s29, s16, 3
	v_add_u32_e32 v149, s29, v148
	v_add_u32_e32 v150, s29, v149
	v_add_u32_e32 v151, s29, v150
	ds_read2_b32 v[100:101], v5 offset1:33
	ds_read2_b32 v[102:103], v5 offset0:66 offset1:99
	ds_read2_b32 v[104:105], v5 offset0:132 offset1:165
	ds_read2_b32 v[106:107], v5 offset0:198 offset1:231
	ds_read2_b32 v[108:109], v5 offset0:8 offset1:41
	ds_read2_b32 v[110:111], v5 offset0:74 offset1:107
	ds_read2_b32 v[112:113], v5 offset0:140 offset1:173
	ds_read2_b32 v[114:115], v5 offset0:206 offset1:239
	ds_read2_b32 v[116:117], v5 offset0:16 offset1:49
	ds_read2_b32 v[118:119], v5 offset0:82 offset1:115
	ds_read2_b32 v[120:121], v5 offset0:148 offset1:181
	ds_read2_b32 v[122:123], v5 offset0:214 offset1:247
	ds_read2_b32 v[124:125], v5 offset0:24 offset1:57
	ds_read2_b32 v[126:127], v5 offset0:90 offset1:123
	ds_read2_b32 v[128:129], v5 offset0:156 offset1:189
	ds_read2_b32 v[130:131], v5 offset0:222 offset1:255
	s_waitcnt lgkmcnt(12)
	v_cvt_pk_bf16_f32 v132, v100, v101
	v_cvt_pk_bf16_f32 v133, v102, v103
	v_cvt_pk_bf16_f32 v134, v104, v105
	v_cvt_pk_bf16_f32 v135, v106, v107
	buffer_store_dwordx4 v[132:135], v148, s[8:11], 0 offen sc1
	s_waitcnt lgkmcnt(8)
	v_cvt_pk_bf16_f32 v136, v108, v109
	v_cvt_pk_bf16_f32 v137, v110, v111
	v_cvt_pk_bf16_f32 v138, v112, v113
	v_cvt_pk_bf16_f32 v139, v114, v115
	buffer_store_dwordx4 v[136:139], v149, s[8:11], 0 offen sc1
	s_waitcnt lgkmcnt(4)
	v_cvt_pk_bf16_f32 v140, v116, v117
	v_cvt_pk_bf16_f32 v141, v118, v119
	v_cvt_pk_bf16_f32 v142, v120, v121
	v_cvt_pk_bf16_f32 v143, v122, v123
	buffer_store_dwordx4 v[140:143], v150, s[8:11], 0 offen sc1
	s_waitcnt lgkmcnt(0)
	v_cvt_pk_bf16_f32 v144, v124, v125
	v_cvt_pk_bf16_f32 v145, v126, v127
	v_cvt_pk_bf16_f32 v146, v128, v129
	v_cvt_pk_bf16_f32 v147, v130, v131
	buffer_store_dwordx4 v[144:147], v151, s[8:11], 0 offen sc1
	s_branch .LBB0_184

; #define LAS __attribute__((address_space(3)))
; __device__ __forceinline__ unsigned pk2(float lo, float hi) { return pg8::cvt_pk_bf16(lo, hi); }
; __device__ __forceinline__ void transpose_item(const float* W, int N, int K, bf16_t* WT, int dstrow0, int srccol0, int k0, LAS float* scr, int lane) {
;     float tv[32];
;     { const float* wp = W + (size_t)(k0 + (lane >> 5)) * N + srccol0 + (lane & 31);
; #pragma unroll
;       for (int i = 0; i < 32; ++i) tv[i] = __builtin_nontemporal_load(wp + (size_t)(2 * i) * N); }
; #pragma unroll
;     for (int i = 0; i < 32; ++i) scr[(2 * i + (lane >> 5)) * 33 + (lane & 31)] = tv[i];
;     asm volatile("s_waitcnt lgkmcnt(0)" ::: "memory");
;     const int c = lane & 7;
; #pragma unroll
;     for (int j = 0; j < 4; ++j) { const int n = (lane >> 3) + 8 * j; const LAS float* s = scr + (8 * c) * 33 + n;
;         u32x4 o; o.x = pk2(s[0 * 33], s[1 * 33]); o.y = pk2(s[2 * 33], s[3 * 33]); o.z = pk2(s[4 * 33], s[5 * 33]); o.w = pk2(s[6 * 33], s[7 * 33]);
;         st16wt(WT, (unsigned)(((dstrow0 + n) * K + k0 + 8 * c) * 2), o); }
;     asm volatile("s_waitcnt lgkmcnt(0)" ::: "memory");
; }
; __device__ __forceinline__ void transposes(const Params& p, LAS unsigned char* lds, int it_begin, int it_end, int gw, int NGW, int lane, int wave) {
;     ...
;         if (r < I_IN) { const int kb = r / 96, nb = r % 96; transpose_item(p.w_in, DIN, 1024, (bf16_t*)(p.ws + WS_WIN), 32 * nb, win_src(32 * nb), 64 * kb, scr, lane); continue; } r -= I_IN;
;         if (r < I_OUT) { const int kb = r / 32, nb = r % 32; transpose_item(p.w_out, 1024, 1024, (bf16_t*)(p.ws + WS_WOUT), 32 * nb, 32 * nb, 64 * kb, scr, lane); continue; } r -= I_OUT;
.Lp1p_done4_2:
	v_mul_u32_u24_e32 v15, s14, v1
	v_add_u32_e32 v15, v15, v0
	s_mov_b32 s22, s12
	s_mov_b32 s23, s13
	s_lshl_b32 s28, s14, 1
	global_load_dword v20, v15, s[22:23] nt
	s_add_u32 s22, s22, s28
	s_addc_u32 s23, s23, 0
	global_load_dword v21, v15, s[22:23] nt
	s_add_u32 s22, s22, s28
	s_addc_u32 s23, s23, 0
	global_load_dword v22, v15, s[22:23] nt
	s_add_u32 s22, s22, s28
	s_addc_u32 s23, s23, 0
	global_load_dword v23, v15, s[22:23] nt
	s_add_u32 s22, s22, s28
	s_addc_u32 s23, s23, 0
	global_load_dword v24, v15, s[22:23] nt
	s_add_u32 s22, s22, s28
	s_addc_u32 s23, s23, 0
	global_load_dword v25, v15, s[22:23] nt
	s_add_u32 s22, s22, s28
	s_addc_u32 s23, s23, 0
	global_load_dword v26, v15, s[22:23] nt
	s_add_u32 s22, s22, s28
	s_addc_u32 s23, s23, 0
	global_load_dword v27, v15, s[22:23] nt
	s_add_u32 s22, s22, s28
	s_addc_u32 s23, s23, 0
	global_load_dword v28, v15, s[22:23] nt
	s_add_u32 s22, s22, s28
	s_addc_u32 s23, s23, 0
	global_load_dword v29, v15, s[22:23] nt
	s_add_u32 s22, s22, s28
	s_addc_u32 s23, s23, 0
	global_load_dword v30, v15, s[22:23] nt
	s_add_u32 s22, s22, s28
	s_addc_u32 s23, s23, 0
	global_load_dword v31, v15, s[22:23] nt
	s_add_u32 s22, s22, s28
	s_addc_u32 s23, s23, 0
	global_load_dword v32, v15, s[22:23] nt
	s_add_u32 s22, s22, s28
	s_addc_u32 s23, s23, 0
	global_load_dword v33, v15, s[22:23] nt
	s_add_u32 s22, s22, s28
	s_addc_u32 s23, s23, 0
	global_load_dword v34, v15, s[22:23] nt
	s_add_u32 s22, s22, s28
	s_addc_u32 s23, s23, 0
	global_load_dword v35, v15, s[22:23] nt
	s_add_u32 s22, s22, s28
	s_addc_u32 s23, s23, 0
	global_load_dword v36, v15, s[22:23] nt
	s_add_u32 s22, s22, s28
	s_addc_u32 s23, s23, 0
	global_load_dword v37, v15, s[22:23] nt
	s_add_u32 s22, s22, s28
	s_addc_u32 s23, s23, 0
	global_load_dword v38, v15, s[22:23] nt
	s_add_u32 s22, s22, s28
	s_addc_u32 s23, s23, 0
	global_load_dword v39, v15, s[22:23] nt
	s_add_u32 s22, s22, s28
	s_addc_u32 s23, s23, 0
	global_load_dword v40, v15, s[22:23] nt
	s_add_u32 s22, s22, s28
	s_addc_u32 s23, s23, 0
	global_load_dword v41, v15, s[22:23] nt
	s_add_u32 s22, s22, s28
	s_addc_u32 s23, s23, 0
	global_load_dword v42, v15, s[22:23] nt
	s_add_u32 s22, s22, s28
	s_addc_u32 s23, s23, 0
	global_load_dword v43, v15, s[22:23] nt
	s_add_u32 s22, s22, s28
	s_addc_u32 s23, s23, 0
	global_load_dword v44, v15, s[22:23] nt
	s_add_u32 s22, s22, s28
	s_addc_u32 s23, s23, 0
	global_load_dword v45, v15, s[22:23] nt
	s_add_u32 s22, s22, s28
	s_addc_u32 s23, s23, 0
	global_load_dword v46, v15, s[22:23] nt
	s_add_u32 s22, s22, s28
	s_addc_u32 s23, s23, 0
	global_load_dword v47, v15, s[22:23] nt
	s_add_u32 s22, s22, s28
	s_addc_u32 s23, s23, 0
	global_load_dword v48, v15, s[22:23] nt
	s_add_u32 s22, s22, s28
	s_addc_u32 s23, s23, 0
	global_load_dword v49, v15, s[22:23] nt
	s_add_u32 s22, s22, s28
	s_addc_u32 s23, s23, 0
	global_load_dword v50, v15, s[22:23] nt
	s_add_u32 s22, s22, s28
	s_addc_u32 s23, s23, 0
	global_load_dword v51, v15, s[22:23] nt
	ds_read2_b32 v[100:101], v5 offset1:33
	ds_read2_b32 v[102:103], v5 offset0:66 offset1:99
	ds_read2_b32 v[104:105], v5 offset0:132 offset1:165
	ds_read2_b32 v[106:107], v5 offset0:198 offset1:231
	ds_read2_b32 v[108:109], v5 offset0:8 offset1:41
	ds_read2_b32 v[110:111], v5 offset0:74 offset1:107
	ds_read2_b32 v[112:113], v5 offset0:140 offset1:173
	ds_read2_b32 v[114:115], v5 offset0:206 offset1:239
	ds_read2_b32 v[116:117], v5 offset0:16 offset1:49
	ds_read2_b32 v[118:119], v5 offset0:82 offset1:115
	ds_read2_b32 v[120:121], v5 offset0:148 offset1:181
	ds_read2_b32 v[122:123], v5 offset0:214 offset1:247
	ds_read2_b32 v[124:125], v5 offset0:24 offset1:57
	ds_read2_b32 v[126:127], v5 offset0:90 offset1:123
	ds_read2_b32 v[128:129], v5 offset0:156 offset1:189
	ds_read2_b32 v[130:131], v5 offset0:222 offset1:255
	s_waitcnt lgkmcnt(12)
	v_cvt_pk_bf16_f32 v132, v100, v101
	v_cvt_pk_bf16_f32 v133, v102, v103
	v_cvt_pk_bf16_f32 v134, v104, v105
	v_cvt_pk_bf16_f32 v135, v106, v107
	buffer_store_dwordx4 v[132:135], v148, s[8:11], 0 offen sc1
	s_waitcnt lgkmcnt(8)
	v_cvt_pk_bf16_f32 v136, v108, v109
	v_cvt_pk_bf16_f32 v137, v110, v111
	v_cvt_pk_bf16_f32 v138, v112, v113
	v_cvt_pk_bf16_f32 v139, v114, v115
	buffer_store_dwordx4 v[136:139], v149, s[8:11], 0 offen sc1
	s_waitcnt lgkmcnt(4)
	v_cvt_pk_bf16_f32 v140, v116, v117
	v_cvt_pk_bf16_f32 v141, v118, v119
	v_cvt_pk_bf16_f32 v142, v120, v121
	v_cvt_pk_bf16_f32 v143, v122, v123
	buffer_store_dwordx4 v[140:143], v150, s[8:11], 0 offen sc1
	s_waitcnt lgkmcnt(0)
	v_cvt_pk_bf16_f32 v144, v124, v125
	v_cvt_pk_bf16_f32 v145, v126, v127
	v_cvt_pk_bf16_f32 v146, v128, v129
	v_cvt_pk_bf16_f32 v147, v130, v131
	buffer_store_dwordx4 v[144:147], v151, s[8:11], 0 offen sc1
	s_waitcnt vmcnt(63)
	ds_write2_b32 v7, v52, v53 offset1:66
	s_waitcnt vmcnt(63)
	ds_write2_b32 v7, v54, v55 offset0:132 offset1:198
	s_waitcnt vmcnt(62)
	ds_write2_b32 v8, v56, v57 offset0:8 offset1:74
	s_waitcnt vmcnt(60)
	ds_write2_b32 v8, v58, v59 offset0:140 offset1:206
	s_waitcnt vmcnt(58)
	ds_write2_b32 v9, v60, v61 offset0:16 offset1:82
	s_waitcnt vmcnt(56)
	ds_write2_b32 v9, v62, v63 offset0:148 offset1:214
	s_waitcnt vmcnt(54)
	ds_write2_b32 v10, v64, v65 offset0:24 offset1:90
	s_waitcnt vmcnt(52)
	ds_write2_b32 v10, v66, v67 offset0:156 offset1:222
	s_waitcnt vmcnt(50)
	ds_write2_b32 v11, v68, v69 offset0:32 offset1:98
	s_waitcnt vmcnt(48)
	ds_write2_b32 v11, v70, v71 offset0:164 offset1:230
	s_waitcnt vmcnt(46)
	ds_write2_b32 v12, v72, v73 offset0:40 offset1:106
	s_waitcnt vmcnt(44)
	ds_write2_b32 v12, v74, v75 offset0:172 offset1:238
	s_waitcnt vmcnt(42)
	ds_write2_b32 v13, v76, v77 offset0:48 offset1:114
	s_waitcnt vmcnt(40)
	ds_write2_b32 v13, v78, v79 offset0:180 offset1:246
	s_waitcnt vmcnt(38)
	ds_write2_b32 v14, v80, v81 offset0:56 offset1:122
	s_waitcnt vmcnt(36)
	ds_write2_b32 v14, v82, v83 offset0:188 offset1:254
	s_waitcnt lgkmcnt(0)
	v_mul_u32_u24_e32 v148, s21, v2
	v_add3_u32 v148, v148, v3, s20
	s_lshl_b32 s29, s21, 3
	v_add_u32_e32 v149, s29, v148
	v_add_u32_e32 v150, s29, v149
	v_add_u32_e32 v151, s29, v150
	s_add_i32 s22, s4, 0x780
	s_addk_i32 s22, 0xfa00
	s_cmpk_lt_u32 s22, 0x200
	s_cbranch_scc0 .Lp1p_up4_3
	s_lshr_b32 s23, s22, 5
	s_and_b32 s28, s22, 31
	s_lshl_b32 s29, s23, 18
	s_lshl_b32 s49, s28, 7
	s_add_i32 s29, s29, s49
	s_add_u32 s17, s42, s29
	s_addc_u32 s18, s43, 0
	s_movk_i32 s19, 0x1000
	s_lshl_b32 s29, s28, 16
	s_lshl_b32 s49, s23, 7
	s_add_i32 s29, s29, s49
	s_add_i32 s20, s29, 0xc00000
	s_movk_i32 s21, 0x800
	s_branch .Lp1p_done4_3

; #define LAS __attribute__((address_space(3)))
; __device__ __forceinline__ unsigned pk2(float lo, float hi) { return pg8::cvt_pk_bf16(lo, hi); }
; __device__ __forceinline__ void transpose_item(const float* W, int N, int K, bf16_t* WT, int dstrow0, int srccol0, int k0, LAS float* scr, int lane) {
;     float tv[32];
;     { const float* wp = W + (size_t)(k0 + (lane >> 5)) * N + srccol0 + (lane & 31);
; #pragma unroll
;       for (int i = 0; i < 32; ++i) tv[i] = __builtin_nontemporal_load(wp + (size_t)(2 * i) * N); }
; #pragma unroll
;     for (int i = 0; i < 32; ++i) scr[(2 * i + (lane >> 5)) * 33 + (lane & 31)] = tv[i];
;     asm volatile("s_waitcnt lgkmcnt(0)" ::: "memory");
;     const int c = lane & 7;
; #pragma unroll
;     for (int j = 0; j < 4; ++j) { const int n = (lane >> 3) + 8 * j; const LAS float* s = scr + (8 * c) * 33 + n;
;         u32x4 o; o.x = pk2(s[0 * 33], s[1 * 33]); o.y = pk2(s[2 * 33], s[3 * 33]); o.z = pk2(s[4 * 33], s[5 * 33]); o.w = pk2(s[6 * 33], s[7 * 33]);
;         st16wt(WT, (unsigned)(((dstrow0 + n) * K + k0 + 8 * c) * 2), o); }
;     asm volatile("s_waitcnt lgkmcnt(0)" ::: "memory");
; }
.Lp1p_done4_3:
	v_mul_u32_u24_e32 v16, s19, v1
	v_add_u32_e32 v16, v16, v0
	s_mov_b32 s22, s17
	s_mov_b32 s23, s18
	s_lshl_b32 s28, s19, 1
	global_load_dword v52, v16, s[22:23] nt
	s_add_u32 s22, s22, s28
	s_addc_u32 s23, s23, 0
	global_load_dword v53, v16, s[22:23] nt
	s_add_u32 s22, s22, s28
	s_addc_u32 s23, s23, 0
	global_load_dword v54, v16, s[22:23] nt
	s_add_u32 s22, s22, s28
	s_addc_u32 s23, s23, 0
	global_load_dword v55, v16, s[22:23] nt
	s_add_u32 s22, s22, s28
	s_addc_u32 s23, s23, 0
	global_load_dword v56, v16, s[22:23] nt
	s_add_u32 s22, s22, s28
	s_addc_u32 s23, s23, 0
	global_load_dword v57, v16, s[22:23] nt
	s_add_u32 s22, s22, s28
	s_addc_u32 s23, s23, 0
	global_load_dword v58, v16, s[22:23] nt
	s_add_u32 s22, s22, s28
	s_addc_u32 s23, s23, 0
	global_load_dword v59, v16, s[22:23] nt
	s_add_u32 s22, s22, s28
	s_addc_u32 s23, s23, 0
	global_load_dword v60, v16, s[22:23] nt
	s_add_u32 s22, s22, s28
	s_addc_u32 s23, s23, 0
	global_load_dword v61, v16, s[22:23] nt
	s_add_u32 s22, s22, s28
	s_addc_u32 s23, s23, 0
	global_load_dword v62, v16, s[22:23] nt
	s_add_u32 s22, s22, s28
	s_addc_u32 s23, s23, 0
	global_load_dword v63, v16, s[22:23] nt
	s_add_u32 s22, s22, s28
	s_addc_u32 s23, s23, 0
	global_load_dword v64, v16, s[22:23] nt
	s_add_u32 s22, s22, s28
	s_addc_u32 s23, s23, 0
	global_load_dword v65, v16, s[22:23] nt
	s_add_u32 s22, s22, s28
	s_addc_u32 s23, s23, 0
	global_load_dword v66, v16, s[22:23] nt
	s_add_u32 s22, s22, s28
	s_addc_u32 s23, s23, 0
	global_load_dword v67, v16, s[22:23] nt
	s_add_u32 s22, s22, s28
	s_addc_u32 s23, s23, 0
	global_load_dword v68, v16, s[22:23] nt
	s_add_u32 s22, s22, s28
	s_addc_u32 s23, s23, 0
	global_load_dword v69, v16, s[22:23] nt
	s_add_u32 s22, s22, s28
	s_addc_u32 s23, s23, 0
	global_load_dword v70, v16, s[22:23] nt
	s_add_u32 s22, s22, s28
	s_addc_u32 s23, s23, 0
	global_load_dword v71, v16, s[22:23] nt
	s_add_u32 s22, s22, s28
	s_addc_u32 s23, s23, 0
	global_load_dword v72, v16, s[22:23] nt
	s_add_u32 s22, s22, s28
	s_addc_u32 s23, s23, 0
	global_load_dword v73, v16, s[22:23] nt
	s_add_u32 s22, s22, s28
	s_addc_u32 s23, s23, 0
	global_load_dword v74, v16, s[22:23] nt
	s_add_u32 s22, s22, s28
	s_addc_u32 s23, s23, 0
	global_load_dword v75, v16, s[22:23] nt
	s_add_u32 s22, s22, s28
	s_addc_u32 s23, s23, 0
	global_load_dword v76, v16, s[22:23] nt
	s_add_u32 s22, s22, s28
	s_addc_u32 s23, s23, 0
	global_load_dword v77, v16, s[22:23] nt
	s_add_u32 s22, s22, s28
	s_addc_u32 s23, s23, 0
	global_load_dword v78, v16, s[22:23] nt
	s_add_u32 s22, s22, s28
	s_addc_u32 s23, s23, 0
	global_load_dword v79, v16, s[22:23] nt
	s_add_u32 s22, s22, s28
	s_addc_u32 s23, s23, 0
	global_load_dword v80, v16, s[22:23] nt
	s_add_u32 s22, s22, s28
	s_addc_u32 s23, s23, 0
	global_load_dword v81, v16, s[22:23] nt
	s_add_u32 s22, s22, s28
	s_addc_u32 s23, s23, 0
	global_load_dword v82, v16, s[22:23] nt
	s_add_u32 s22, s22, s28
	s_addc_u32 s23, s23, 0
	global_load_dword v83, v16, s[22:23] nt
	ds_read2_b32 v[100:101], v5 offset1:33
	ds_read2_b32 v[102:103], v5 offset0:66 offset1:99
	ds_read2_b32 v[104:105], v5 offset0:132 offset1:165
	ds_read2_b32 v[106:107], v5 offset0:198 offset1:231
	ds_read2_b32 v[108:109], v5 offset0:8 offset1:41
	ds_read2_b32 v[110:111], v5 offset0:74 offset1:107
	ds_read2_b32 v[112:113], v5 offset0:140 offset1:173
	ds_read2_b32 v[114:115], v5 offset0:206 offset1:239
	ds_read2_b32 v[116:117], v5 offset0:16 offset1:49
	ds_read2_b32 v[118:119], v5 offset0:82 offset1:115
	ds_read2_b32 v[120:121], v5 offset0:148 offset1:181
	ds_read2_b32 v[122:123], v5 offset0:214 offset1:247
	ds_read2_b32 v[124:125], v5 offset0:24 offset1:57
	ds_read2_b32 v[126:127], v5 offset0:90 offset1:123
	ds_read2_b32 v[128:129], v5 offset0:156 offset1:189
	ds_read2_b32 v[130:131], v5 offset0:222 offset1:255
	s_waitcnt lgkmcnt(12)
	v_cvt_pk_bf16_f32 v132, v100, v101
	v_cvt_pk_bf16_f32 v133, v102, v103
	v_cvt_pk_bf16_f32 v134, v104, v105
	v_cvt_pk_bf16_f32 v135, v106, v107
	buffer_store_dwordx4 v[132:135], v148, s[8:11], 0 offen sc1
	s_waitcnt lgkmcnt(8)
	v_cvt_pk_bf16_f32 v136, v108, v109
	v_cvt_pk_bf16_f32 v137, v110, v111
	v_cvt_pk_bf16_f32 v138, v112, v113
	v_cvt_pk_bf16_f32 v139, v114, v115
	buffer_store_dwordx4 v[136:139], v149, s[8:11], 0 offen sc1
	s_waitcnt lgkmcnt(4)
	v_cvt_pk_bf16_f32 v140, v116, v117
	v_cvt_pk_bf16_f32 v141, v118, v119
	v_cvt_pk_bf16_f32 v142, v120, v121
	v_cvt_pk_bf16_f32 v143, v122, v123
	buffer_store_dwordx4 v[140:143], v150, s[8:11], 0 offen sc1
	s_waitcnt lgkmcnt(0)
	v_cvt_pk_bf16_f32 v144, v124, v125
	v_cvt_pk_bf16_f32 v145, v126, v127
	v_cvt_pk_bf16_f32 v146, v128, v129
	v_cvt_pk_bf16_f32 v147, v130, v131
	buffer_store_dwordx4 v[144:147], v151, s[8:11], 0 offen sc1
	s_waitcnt vmcnt(63)
	ds_write2_b32 v7, v20, v21 offset1:66
	s_waitcnt vmcnt(63)
	ds_write2_b32 v7, v22, v23 offset0:132 offset1:198
	s_waitcnt vmcnt(63)
	ds_write2_b32 v8, v24, v25 offset0:8 offset1:74
	s_waitcnt vmcnt(63)
	ds_write2_b32 v8, v26, v27 offset0:140 offset1:206
	s_waitcnt vmcnt(62)
	ds_write2_b32 v9, v28, v29 offset0:16 offset1:82
	s_waitcnt vmcnt(60)
	ds_write2_b32 v9, v30, v31 offset0:148 offset1:214
	s_waitcnt vmcnt(58)
	ds_write2_b32 v10, v32, v33 offset0:24 offset1:90
	s_waitcnt vmcnt(56)
	ds_write2_b32 v10, v34, v35 offset0:156 offset1:222
	s_waitcnt vmcnt(54)
	ds_write2_b32 v11, v36, v37 offset0:32 offset1:98
	s_waitcnt vmcnt(52)
	ds_write2_b32 v11, v38, v39 offset0:164 offset1:230
	s_waitcnt vmcnt(50)
; #define LAS __attribute__((address_space(3)))
; __device__ __forceinline__ unsigned pk2(float lo, float hi) { return pg8::cvt_pk_bf16(lo, hi); }
; __device__ __forceinline__ int wup_src(int p0) { const int j = p0 >> 8, c = p0 & 255; return (c < 128) ? 128 * j + c : DFF + 128 * j + (c - 128); }
; __device__ __forceinline__ void transpose_item(const float* W, int N, int K, bf16_t* WT, int dstrow0, int srccol0, int k0, LAS float* scr, int lane) {
;     float tv[32];
;     { const float* wp = W + (size_t)(k0 + (lane >> 5)) * N + srccol0 + (lane & 31);
; #pragma unroll
;       for (int i = 0; i < 32; ++i) tv[i] = __builtin_nontemporal_load(wp + (size_t)(2 * i) * N); }
; #pragma unroll
;     for (int i = 0; i < 32; ++i) scr[(2 * i + (lane >> 5)) * 33 + (lane & 31)] = tv[i];
;     asm volatile("s_waitcnt lgkmcnt(0)" ::: "memory");
;     const int c = lane & 7;
; #pragma unroll
;     for (int j = 0; j < 4; ++j) { const int n = (lane >> 3) + 8 * j; const LAS float* s = scr + (8 * c) * 33 + n;
;         u32x4 o; o.x = pk2(s[0 * 33], s[1 * 33]); o.y = pk2(s[2 * 33], s[3 * 33]); o.z = pk2(s[4 * 33], s[5 * 33]); o.w = pk2(s[6 * 33], s[7 * 33]);
;         st16wt(WT, (unsigned)(((dstrow0 + n) * K + k0 + 8 * c) * 2), o); }
;     asm volatile("s_waitcnt lgkmcnt(0)" ::: "memory");
; }
; __device__ __forceinline__ void transposes(const Params& p, LAS unsigned char* lds, int it_begin, int it_end, int gw, int NGW, int lane, int wave) {
;     ...
;     for (int it = it_begin + gw; it < it_end; it += NGW) {
;         int r = it;
;         if (r < I_IN) { const int kb = r / 96, nb = r % 96; transpose_item(p.w_in, DIN, 1024, (bf16_t*)(p.ws + WS_WIN), 32 * nb, win_src(32 * nb), 64 * kb, scr, lane); continue; } r -= I_IN;
;         if (r < I_OUT) { const int kb = r / 32, nb = r % 32; transpose_item(p.w_out, 1024, 1024, (bf16_t*)(p.ws + WS_WOUT), 32 * nb, 32 * nb, 64 * kb, scr, lane); continue; } r -= I_OUT;
;         if (r < I_UP) { const int kb = r / 176, nb = r % 176; transpose_item(p.w_up, 2 * DFF, 1024, (bf16_t*)(p.ws + WS_WUP), 32 * nb, wup_src(32 * nb), 64 * kb, scr, lane); continue; } r -= I_UP;
;         { const int kb = r / 32, nb = r % 32; transpose_item(p.w_down, 1024, DFF, (bf16_t*)(p.ws + WS_WDOWN), 32 * nb, 32 * nb, 64 * kb, scr, lane); }
	ds_write2_b32 v12, v40, v41 offset0:40 offset1:106
	s_waitcnt vmcnt(48)
	ds_write2_b32 v12, v42, v43 offset0:172 offset1:238
	s_waitcnt vmcnt(46)
	ds_write2_b32 v13, v44, v45 offset0:48 offset1:114
	s_waitcnt vmcnt(44)
	ds_write2_b32 v13, v46, v47 offset0:180 offset1:246
	s_waitcnt vmcnt(42)
	ds_write2_b32 v14, v48, v49 offset0:56 offset1:122
	s_waitcnt vmcnt(40)
	ds_write2_b32 v14, v50, v51 offset0:188 offset1:254
	s_waitcnt lgkmcnt(0)
	v_mul_u32_u24_e32 v148, s16, v2
	v_add3_u32 v148, v148, v3, s15
	s_lshl_b32 s29, s16, 3
	v_add_u32_e32 v149, s29, v148
	v_add_u32_e32 v150, s29, v149
	v_add_u32_e32 v151, s29, v150
	ds_read2_b32 v[100:101], v5 offset1:33
	ds_read2_b32 v[102:103], v5 offset0:66 offset1:99
	ds_read2_b32 v[104:105], v5 offset0:132 offset1:165
	ds_read2_b32 v[106:107], v5 offset0:198 offset1:231
	ds_read2_b32 v[108:109], v5 offset0:8 offset1:41
	ds_read2_b32 v[110:111], v5 offset0:74 offset1:107
	ds_read2_b32 v[112:113], v5 offset0:140 offset1:173
	ds_read2_b32 v[114:115], v5 offset0:206 offset1:239
	ds_read2_b32 v[116:117], v5 offset0:16 offset1:49
	ds_read2_b32 v[118:119], v5 offset0:82 offset1:115
	ds_read2_b32 v[120:121], v5 offset0:148 offset1:181
	ds_read2_b32 v[122:123], v5 offset0:214 offset1:247
	ds_read2_b32 v[124:125], v5 offset0:24 offset1:57
	ds_read2_b32 v[126:127], v5 offset0:90 offset1:123
	ds_read2_b32 v[128:129], v5 offset0:156 offset1:189
	ds_read2_b32 v[130:131], v5 offset0:222 offset1:255
	s_waitcnt lgkmcnt(12)
	v_cvt_pk_bf16_f32 v132, v100, v101
	v_cvt_pk_bf16_f32 v133, v102, v103
	v_cvt_pk_bf16_f32 v134, v104, v105
	v_cvt_pk_bf16_f32 v135, v106, v107
	buffer_store_dwordx4 v[132:135], v148, s[8:11], 0 offen sc1
	s_waitcnt lgkmcnt(8)
	v_cvt_pk_bf16_f32 v136, v108, v109
	v_cvt_pk_bf16_f32 v137, v110, v111
	v_cvt_pk_bf16_f32 v138, v112, v113
	v_cvt_pk_bf16_f32 v139, v114, v115
	buffer_store_dwordx4 v[136:139], v149, s[8:11], 0 offen sc1
	s_waitcnt lgkmcnt(4)
	v_cvt_pk_bf16_f32 v140, v116, v117
	v_cvt_pk_bf16_f32 v141, v118, v119
	v_cvt_pk_bf16_f32 v142, v120, v121
	v_cvt_pk_bf16_f32 v143, v122, v123
	buffer_store_dwordx4 v[140:143], v150, s[8:11], 0 offen sc1
	s_waitcnt lgkmcnt(0)
	v_cvt_pk_bf16_f32 v144, v124, v125
	v_cvt_pk_bf16_f32 v145, v126, v127
	v_cvt_pk_bf16_f32 v146, v128, v129
	v_cvt_pk_bf16_f32 v147, v130, v131
	buffer_store_dwordx4 v[144:147], v151, s[8:11], 0 offen sc1
	s_waitcnt vmcnt(38)
	ds_write2_b32 v7, v52, v53 offset1:66
	s_waitcnt vmcnt(36)
	ds_write2_b32 v7, v54, v55 offset0:132 offset1:198
	s_waitcnt vmcnt(34)
	ds_write2_b32 v8, v56, v57 offset0:8 offset1:74
	s_waitcnt vmcnt(32)
	ds_write2_b32 v8, v58, v59 offset0:140 offset1:206
	s_waitcnt vmcnt(30)
	ds_write2_b32 v9, v60, v61 offset0:16 offset1:82
	s_waitcnt vmcnt(28)
	ds_write2_b32 v9, v62, v63 offset0:148 offset1:214
	s_waitcnt vmcnt(26)
	ds_write2_b32 v10, v64, v65 offset0:24 offset1:90
	s_waitcnt vmcnt(24)
	ds_write2_b32 v10, v66, v67 offset0:156 offset1:222
	s_waitcnt vmcnt(22)
	ds_write2_b32 v11, v68, v69 offset0:32 offset1:98
	s_waitcnt vmcnt(20)
	ds_write2_b32 v11, v70, v71 offset0:164 offset1:230
	s_waitcnt vmcnt(18)
	ds_write2_b32 v12, v72, v73 offset0:40 offset1:106
	s_waitcnt vmcnt(16)
	ds_write2_b32 v12, v74, v75 offset0:172 offset1:238
	s_waitcnt vmcnt(14)
	ds_write2_b32 v13, v76, v77 offset0:48 offset1:114
	s_waitcnt vmcnt(12)
	ds_write2_b32 v13, v78, v79 offset0:180 offset1:246
	s_waitcnt vmcnt(10)
	ds_write2_b32 v14, v80, v81 offset0:56 offset1:122
	s_waitcnt vmcnt(8)
	ds_write2_b32 v14, v82, v83 offset0:188 offset1:254
	s_waitcnt lgkmcnt(0)
	v_mul_u32_u24_e32 v148, s21, v2
	v_add3_u32 v148, v148, v3, s20
	s_lshl_b32 s29, s21, 3
	v_add_u32_e32 v149, s29, v148
	v_add_u32_e32 v150, s29, v149
	v_add_u32_e32 v151, s29, v150
	ds_read2_b32 v[100:101], v5 offset1:33
	ds_read2_b32 v[102:103], v5 offset0:66 offset1:99
	ds_read2_b32 v[104:105], v5 offset0:132 offset1:165
	ds_read2_b32 v[106:107], v5 offset0:198 offset1:231
	ds_read2_b32 v[108:109], v5 offset0:8 offset1:41
	ds_read2_b32 v[110:111], v5 offset0:74 offset1:107
	ds_read2_b32 v[112:113], v5 offset0:140 offset1:173
	ds_read2_b32 v[114:115], v5 offset0:206 offset1:239
	ds_read2_b32 v[116:117], v5 offset0:16 offset1:49
	ds_read2_b32 v[118:119], v5 offset0:82 offset1:115
	ds_read2_b32 v[120:121], v5 offset0:148 offset1:181
	ds_read2_b32 v[122:123], v5 offset0:214 offset1:247
	ds_read2_b32 v[124:125], v5 offset0:24 offset1:57
	ds_read2_b32 v[126:127], v5 offset0:90 offset1:123
	ds_read2_b32 v[128:129], v5 offset0:156 offset1:189
	ds_read2_b32 v[130:131], v5 offset0:222 offset1:255
	s_waitcnt lgkmcnt(12)
	v_cvt_pk_bf16_f32 v132, v100, v101
	v_cvt_pk_bf16_f32 v133, v102, v103
	v_cvt_pk_bf16_f32 v134, v104, v105
	v_cvt_pk_bf16_f32 v135, v106, v107
	buffer_store_dwordx4 v[132:135], v148, s[8:11], 0 offen sc1
	s_waitcnt lgkmcnt(8)
	v_cvt_pk_bf16_f32 v136, v108, v109
	v_cvt_pk_bf16_f32 v137, v110, v111
	v_cvt_pk_bf16_f32 v138, v112, v113
	v_cvt_pk_bf16_f32 v139, v114, v115
	buffer_store_dwordx4 v[136:139], v149, s[8:11], 0 offen sc1
	s_waitcnt lgkmcnt(4)
	v_cvt_pk_bf16_f32 v140, v116, v117
	v_cvt_pk_bf16_f32 v141, v118, v119
	v_cvt_pk_bf16_f32 v142, v120, v121
	v_cvt_pk_bf16_f32 v143, v122, v123
	buffer_store_dwordx4 v[140:143], v150, s[8:11], 0 offen sc1
	s_waitcnt lgkmcnt(0)
	v_cvt_pk_bf16_f32 v144, v124, v125
	v_cvt_pk_bf16_f32 v145, v126, v127
	v_cvt_pk_bf16_f32 v146, v128, v129
	v_cvt_pk_bf16_f32 v147, v130, v131
	buffer_store_dwordx4 v[144:147], v151, s[8:11], 0 offen sc1
	s_branch .LBB0_184
